# adds the hand-written Ph5 epilogue (loader-side W_up row permutation, v_permlane16_swap pairing, dword stores) to the lean attention loop; every hand-written region followed by code kept at its 64-byt
# speedup vs baseline: 1.0069x; 1.0069x over previous
.Lg1_noraise:
.Lg1_loop:
	v_add_u32_e32 v246, s38, v242
	v_add_u32_e32 v247, s38, v243
	v_add_u32_e32 v248, s38, v244
	v_add_u32_e32 v249, s38, v245
	ds_read_b128 v[144:147], v246
	ds_read_b128 v[148:151], v246 offset:2048
	ds_read_b128 v[160:163], v248
	ds_read_b128 v[164:167], v248 offset:2048
	ds_read_b128 v[168:171], v248 offset:4096
	s_waitcnt lgkmcnt(2)
	v_mfma_f32_32x32x16_bf16 v[80:95], v[144:147], v[160:163], v[80:95]
	global_load_dwordx4 v[96:99], v138, s[28:29]
	ds_read_b128 v[152:155], v247
	v_mfma_f32_32x32x16_bf16 v[32:47], v[148:151], v[160:163], v[32:47]
	global_load_dwordx4 v[100:103], v139, s[28:29]
	ds_read_b128 v[156:159], v247 offset:2048
	s_waitcnt lgkmcnt(3)
	v_mfma_f32_32x32x16_bf16 v[64:79], v[144:147], v[164:167], v[64:79]
	global_load_dwordx4 v[104:107], v140, s[28:29]
	ds_read_b128 v[172:175], v249
	v_mfma_f32_32x32x16_bf16 v[16:31], v[148:151], v[164:167], v[16:31]
	global_load_dwordx4 v[108:111], v141, s[28:29]
	ds_read_b128 v[176:179], v249 offset:2048
	s_waitcnt lgkmcnt(4)
	v_mfma_f32_32x32x16_bf16 v[48:63], v[144:147], v[168:171], v[48:63]
	global_load_dwordx4 v[112:115], v138, s[36:37]
	ds_read_b128 v[180:183], v249 offset:4096
	v_mfma_f32_32x32x16_bf16 v[0:15], v[148:151], v[168:171], v[0:15]
	global_load_dwordx4 v[116:119], v139, s[36:37]
	v_xad_u32 v246, v242, 64, s39
	v_xad_u32 v248, v244, 64, s39
	s_waitcnt lgkmcnt(2)
	v_mfma_f32_32x32x16_bf16 v[80:95], v[152:155], v[172:175], v[80:95]
	global_load_dwordx4 v[120:123], v140, s[36:37]
	ds_read_b128 v[144:147], v246
	v_mfma_f32_32x32x16_bf16 v[32:47], v[156:159], v[172:175], v[32:47]
	global_load_dwordx4 v[124:127], v141, s[36:37]
	ds_read_b128 v[148:151], v246 offset:2048
	s_waitcnt lgkmcnt(3)
	v_mfma_f32_32x32x16_bf16 v[64:79], v[152:155], v[176:179], v[64:79]
	global_load_dwordx4 v[128:131], v142, s[36:37]
	ds_read_b128 v[160:163], v248
	v_mfma_f32_32x32x16_bf16 v[16:31], v[156:159], v[176:179], v[16:31]
	global_load_dwordx4 v[132:135], v143, s[36:37]
	ds_read_b128 v[164:167], v248 offset:2048
	s_waitcnt lgkmcnt(4)
	v_mfma_f32_32x32x16_bf16 v[48:63], v[152:155], v[180:183], v[48:63]
	ds_read_b128 v[168:171], v248 offset:4096
	v_mfma_f32_32x32x16_bf16 v[0:15], v[156:159], v[180:183], v[0:15]
	s_barrier
	v_xad_u32 v247, v243, 64, s39
	v_xad_u32 v249, v245, 64, s39
	s_waitcnt lgkmcnt(2)
	v_mfma_f32_32x32x16_bf16 v[80:95], v[144:147], v[160:163], v[80:95]
	ds_read_b128 v[152:155], v247
	v_mfma_f32_32x32x16_bf16 v[32:47], v[148:151], v[160:163], v[32:47]
	ds_read_b128 v[156:159], v247 offset:2048
	s_waitcnt lgkmcnt(3)
	v_mfma_f32_32x32x16_bf16 v[64:79], v[144:147], v[164:167], v[64:79]
	ds_read_b128 v[172:175], v249
	s_waitcnt vmcnt(9)
	ds_write_b128 v250, v[96:99]
	v_mfma_f32_32x32x16_bf16 v[16:31], v[148:151], v[164:167], v[16:31]
	ds_read_b128 v[176:179], v249 offset:2048
	s_waitcnt vmcnt(8)
	ds_write_b128 v250, v[100:103] offset:2048
	s_waitcnt lgkmcnt(6)
	v_mfma_f32_32x32x16_bf16 v[48:63], v[144:147], v[168:171], v[48:63]
	ds_read_b128 v[180:183], v249 offset:4096
	s_waitcnt vmcnt(7)
	ds_write_b128 v250, v[104:107] offset:4096
	v_mfma_f32_32x32x16_bf16 v[0:15], v[148:151], v[168:171], v[0:15]
	s_waitcnt vmcnt(6)
	ds_write_b128 v250, v[108:111] offset:6144
	s_waitcnt lgkmcnt(6)
	v_mfma_f32_32x32x16_bf16 v[80:95], v[152:155], v[172:175], v[80:95]
	s_waitcnt vmcnt(5)
	ds_write_b128 v250, v[112:115] offset:8192
	v_mfma_f32_32x32x16_bf16 v[32:47], v[156:159], v[172:175], v[32:47]
	s_waitcnt vmcnt(4)
	ds_write_b128 v250, v[116:119] offset:10240
	s_waitcnt lgkmcnt(6)
	v_mfma_f32_32x32x16_bf16 v[64:79], v[152:155], v[176:179], v[64:79]
	s_waitcnt vmcnt(3)
	ds_write_b128 v250, v[120:123] offset:12288
	v_mfma_f32_32x32x16_bf16 v[16:31], v[156:159], v[176:179], v[16:31]
	s_waitcnt vmcnt(2)
	ds_write_b128 v250, v[124:127] offset:14336
	s_waitcnt lgkmcnt(6)
	v_mfma_f32_32x32x16_bf16 v[48:63], v[152:155], v[180:183], v[48:63]
	s_waitcnt vmcnt(1)
	ds_write_b128 v250, v[128:131] offset:16384
	v_mfma_f32_32x32x16_bf16 v[0:15], v[156:159], v[180:183], v[0:15]
	s_waitcnt vmcnt(0)
	ds_write_b128 v250, v[132:135] offset:18432
	s_add_u32 s28, s28, 0x80
	s_addc_u32 s29, s29, 0
	s_add_u32 s36, s36, 0x80
	s_addc_u32 s37, s37, 0
	s_sub_i32 s38, s38, 0x5000
	s_cmp_lt_i32 s38, 0
	s_cselect_b32 s40, 0xf000, 0
	s_add_i32 s38, s38, s40
	s_sub_i32 s39, s39, 0x5000
	s_cmp_lt_i32 s39, 0
	s_cselect_b32 s40, 0xf000, 0
	s_add_i32 s39, s39, s40
	v_subrev_u32_e32 v196, 0x5000, v250
	v_add_u32_e32 v198, 0xa000, v250
	v_min_u32_e32 v250, v196, v198
	s_add_i32 s5, s5, 1
	s_cmp_lt_u32 s5, 15
	s_waitcnt lgkmcnt(0)
	s_barrier
	s_cbranch_scc1 .Lg1_loop
	v_add_u32_e32 v246, s38, v242
	v_add_u32_e32 v247, s38, v243
	v_add_u32_e32 v248, s38, v244
	v_add_u32_e32 v249, s38, v245
	ds_read_b128 v[144:147], v246
	ds_read_b128 v[148:151], v246 offset:2048
	ds_read_b128 v[160:163], v248
	ds_read_b128 v[164:167], v248 offset:2048
	ds_read_b128 v[168:171], v248 offset:4096
	s_waitcnt lgkmcnt(2)
	v_mfma_f32_32x32x16_bf16 v[80:95], v[144:147], v[160:163], v[80:95]
	ds_read_b128 v[152:155], v247
	v_mfma_f32_32x32x16_bf16 v[32:47], v[148:151], v[160:163], v[32:47]
	ds_read_b128 v[156:159], v247 offset:2048
	s_waitcnt lgkmcnt(3)
	v_mfma_f32_32x32x16_bf16 v[64:79], v[144:147], v[164:167], v[64:79]
	ds_read_b128 v[172:175], v249
	v_mfma_f32_32x32x16_bf16 v[16:31], v[148:151], v[164:167], v[16:31]
	ds_read_b128 v[176:179], v249 offset:2048
	s_waitcnt lgkmcnt(4)
	v_mfma_f32_32x32x16_bf16 v[48:63], v[144:147], v[168:171], v[48:63]
	ds_read_b128 v[180:183], v249 offset:4096
	v_mfma_f32_32x32x16_bf16 v[0:15], v[148:151], v[168:171], v[0:15]
	v_xad_u32 v246, v242, 64, s39
	v_xad_u32 v248, v244, 64, s39
	s_waitcnt lgkmcnt(2)
	v_mfma_f32_32x32x16_bf16 v[80:95], v[152:155], v[172:175], v[80:95]
	ds_read_b128 v[144:147], v246
	v_mfma_f32_32x32x16_bf16 v[32:47], v[156:159], v[172:175], v[32:47]
	ds_read_b128 v[148:151], v246 offset:2048
	s_waitcnt lgkmcnt(3)
	v_mfma_f32_32x32x16_bf16 v[64:79], v[152:155], v[176:179], v[64:79]
	ds_read_b128 v[160:163], v248
	v_mfma_f32_32x32x16_bf16 v[16:31], v[156:159], v[176:179], v[16:31]
	ds_read_b128 v[164:167], v248 offset:2048
	s_waitcnt lgkmcnt(4)
	v_mfma_f32_32x32x16_bf16 v[48:63], v[152:155], v[180:183], v[48:63]
	ds_read_b128 v[168:171], v248 offset:4096
	v_mfma_f32_32x32x16_bf16 v[0:15], v[156:159], v[180:183], v[0:15]
	v_xad_u32 v247, v243, 64, s39
	v_xad_u32 v249, v245, 64, s39
	s_waitcnt lgkmcnt(2)
	v_mfma_f32_32x32x16_bf16 v[80:95], v[144:147], v[160:163], v[80:95]
	ds_read_b128 v[152:155], v247
	v_mfma_f32_32x32x16_bf16 v[32:47], v[148:151], v[160:163], v[32:47]
	ds_read_b128 v[156:159], v247 offset:2048
	s_waitcnt lgkmcnt(3)
	v_mfma_f32_32x32x16_bf16 v[64:79], v[144:147], v[164:167], v[64:79]
	ds_read_b128 v[172:175], v249
	v_mfma_f32_32x32x16_bf16 v[16:31], v[148:151], v[164:167], v[16:31]
	ds_read_b128 v[176:179], v249 offset:2048
	s_waitcnt lgkmcnt(4)
	v_mfma_f32_32x32x16_bf16 v[48:63], v[144:147], v[168:171], v[48:63]
	ds_read_b128 v[180:183], v249 offset:4096
	v_mfma_f32_32x32x16_bf16 v[0:15], v[148:151], v[168:171], v[0:15]
	s_waitcnt lgkmcnt(2)
	v_mfma_f32_32x32x16_bf16 v[80:95], v[152:155], v[172:175], v[80:95]
	v_mfma_f32_32x32x16_bf16 v[32:47], v[156:159], v[172:175], v[32:47]
	s_waitcnt lgkmcnt(1)
	v_mfma_f32_32x32x16_bf16 v[64:79], v[152:155], v[176:179], v[64:79]
	v_mfma_f32_32x32x16_bf16 v[16:31], v[156:159], v[176:179], v[16:31]
	s_waitcnt lgkmcnt(0)
	v_mfma_f32_32x32x16_bf16 v[48:63], v[152:155], v[180:183], v[48:63]
	v_mfma_f32_32x32x16_bf16 v[0:15], v[156:159], v[180:183], v[0:15]
	s_setprio 0
	s_nop 7
	s_nop 7
	.p2align 6
	s_nop 0
	s_nop 0

.Lg4_noraise:
.Lg4_loop:
	v_add_u32_e32 v190, s40, v186
	v_add_u32_e32 v191, s40, v187
	v_add_u32_e32 v250, s40, v188
	v_add_u32_e32 v251, s40, v189
	ds_read_b128 v[200:203], v190
	ds_read_b128 v[204:207], v190 offset:2048
	ds_read_b128 v[222:225], v250
	ds_read_b128 v[226:229], v250 offset:2048
	ds_read_b128 v[230:233], v250 offset:4096
	ds_read_b128 v[234:237], v250 offset:6144
	s_waitcnt lgkmcnt(3)
	v_mfma_f32_32x32x16_bf16 v[112:127], v[200:203], v[222:225], v[112:127]
	global_load_dwordx4 v[128:131], v176, s[28:29]
	ds_read_b128 v[208:211], v191
	v_mfma_f32_32x32x16_bf16 v[48:63], v[204:207], v[222:225], v[48:63]
	global_load_dwordx4 v[132:135], v177, s[28:29]
	ds_read_b128 v[212:215], v191 offset:2048
	s_waitcnt lgkmcnt(4)
	v_mfma_f32_32x32x16_bf16 v[96:111], v[200:203], v[226:229], v[96:111]
	global_load_dwordx4 v[136:139], v178, s[28:29]
	ds_read_b128 v[238:241], v251
	v_mfma_f32_32x32x16_bf16 v[32:47], v[204:207], v[226:229], v[32:47]
	global_load_dwordx4 v[140:143], v179, s[28:29]
	ds_read_b128 v[242:245], v251 offset:2048
	s_waitcnt lgkmcnt(5)
	v_mfma_f32_32x32x16_bf16 v[80:95], v[200:203], v[230:233], v[80:95]
	global_load_dwordx4 v[144:147], v176, s[38:39]
	ds_read_b128 v[246:249], v251 offset:4096
	v_mfma_f32_32x32x16_bf16 v[16:31], v[204:207], v[230:233], v[16:31]
	global_load_dwordx4 v[148:151], v177, s[38:39]
	ds_read_b128 v[192:195], v251 offset:6144
	s_waitcnt lgkmcnt(6)
	v_mfma_f32_32x32x16_bf16 v[64:79], v[200:203], v[234:237], v[64:79]
	global_load_dwordx4 v[152:155], v178, s[38:39]
	v_mfma_f32_32x32x16_bf16 v[0:15], v[204:207], v[234:237], v[0:15]
	global_load_dwordx4 v[156:159], v179, s[38:39]
	v_xad_u32 v190, v186, 64, s41
	v_xad_u32 v250, v188, 64, s41
	s_waitcnt lgkmcnt(3)
	v_mfma_f32_32x32x16_bf16 v[112:127], v[208:211], v[238:241], v[112:127]
	global_load_dwordx4 v[160:163], v180, s[38:39]
	ds_read_b128 v[200:203], v190
	v_mfma_f32_32x32x16_bf16 v[48:63], v[212:215], v[238:241], v[48:63]
	global_load_dwordx4 v[164:167], v181, s[38:39]
	ds_read_b128 v[204:207], v190 offset:2048
	s_waitcnt lgkmcnt(4)
	v_mfma_f32_32x32x16_bf16 v[96:111], v[208:211], v[242:245], v[96:111]
	global_load_dwordx4 v[168:171], v182, s[38:39]
	ds_read_b128 v[222:225], v250
	v_mfma_f32_32x32x16_bf16 v[32:47], v[212:215], v[242:245], v[32:47]
	global_load_dwordx4 v[172:175], v184, s[38:39]
	ds_read_b128 v[226:229], v250 offset:2048
	s_waitcnt lgkmcnt(5)
	v_mfma_f32_32x32x16_bf16 v[80:95], v[208:211], v[246:249], v[80:95]
	ds_read_b128 v[230:233], v250 offset:4096
	v_mfma_f32_32x32x16_bf16 v[16:31], v[212:215], v[246:249], v[16:31]
	ds_read_b128 v[234:237], v250 offset:6144
	s_waitcnt lgkmcnt(6)
	v_mfma_f32_32x32x16_bf16 v[64:79], v[208:211], v[192:195], v[64:79]
	v_mfma_f32_32x32x16_bf16 v[0:15], v[212:215], v[192:195], v[0:15]
	s_barrier
	v_xad_u32 v191, v187, 64, s41
	v_xad_u32 v251, v189, 64, s41
	s_waitcnt lgkmcnt(3)
	v_mfma_f32_32x32x16_bf16 v[112:127], v[200:203], v[222:225], v[112:127]
	ds_read_b128 v[208:211], v191
	v_mfma_f32_32x32x16_bf16 v[48:63], v[204:207], v[222:225], v[48:63]
	ds_read_b128 v[212:215], v191 offset:2048
	s_waitcnt lgkmcnt(4)
	v_mfma_f32_32x32x16_bf16 v[96:111], v[200:203], v[226:229], v[96:111]
	ds_read_b128 v[238:241], v251
	s_waitcnt vmcnt(11)
	ds_write_b128 v185, v[128:131]
	v_mfma_f32_32x32x16_bf16 v[32:47], v[204:207], v[226:229], v[32:47]
	ds_read_b128 v[242:245], v251 offset:2048
	s_waitcnt vmcnt(10)
	ds_write_b128 v185, v[132:135] offset:2048
	s_waitcnt lgkmcnt(7)
	v_mfma_f32_32x32x16_bf16 v[80:95], v[200:203], v[230:233], v[80:95]
	ds_read_b128 v[246:249], v251 offset:4096
	s_waitcnt vmcnt(9)
	ds_write_b128 v185, v[136:139] offset:4096
	v_mfma_f32_32x32x16_bf16 v[16:31], v[204:207], v[230:233], v[16:31]
	ds_read_b128 v[192:195], v251 offset:6144
	s_waitcnt vmcnt(8)
	ds_write_b128 v185, v[140:143] offset:6144
	s_waitcnt lgkmcnt(10)
	v_mfma_f32_32x32x16_bf16 v[64:79], v[200:203], v[234:237], v[64:79]
	s_waitcnt vmcnt(7)
	ds_write_b128 v185, v[144:147] offset:8192
	v_mfma_f32_32x32x16_bf16 v[0:15], v[204:207], v[234:237], v[0:15]
	s_waitcnt vmcnt(6)
	ds_write_b128 v185, v[148:151] offset:10240
	s_waitcnt lgkmcnt(9)
	v_mfma_f32_32x32x16_bf16 v[112:127], v[208:211], v[238:241], v[112:127]
	s_waitcnt vmcnt(5)
	ds_write_b128 v185, v[152:155] offset:12288
	v_mfma_f32_32x32x16_bf16 v[48:63], v[212:215], v[238:241], v[48:63]
	s_waitcnt vmcnt(4)
	ds_write_b128 v185, v[156:159] offset:14336
	s_waitcnt lgkmcnt(9)
	v_mfma_f32_32x32x16_bf16 v[96:111], v[208:211], v[242:245], v[96:111]
	s_waitcnt vmcnt(3)
	ds_write_b128 v185, v[160:163] offset:16384
	v_mfma_f32_32x32x16_bf16 v[32:47], v[212:215], v[242:245], v[32:47]
	s_waitcnt vmcnt(2)
	ds_write_b128 v185, v[164:167] offset:18432
	s_waitcnt lgkmcnt(9)
	v_mfma_f32_32x32x16_bf16 v[80:95], v[208:211], v[246:249], v[80:95]
	s_waitcnt vmcnt(1)
	ds_write_b128 v185, v[168:171] offset:20480
	v_mfma_f32_32x32x16_bf16 v[16:31], v[212:215], v[246:249], v[16:31]
	s_waitcnt vmcnt(0)
	ds_write_b128 v185, v[172:175] offset:22528
	s_waitcnt lgkmcnt(9)
	v_mfma_f32_32x32x16_bf16 v[64:79], v[208:211], v[192:195], v[64:79]
	v_mfma_f32_32x32x16_bf16 v[0:15], v[212:215], v[192:195], v[0:15]
	s_add_u32 s28, s28, 0x80
	s_addc_u32 s29, s29, 0
	s_add_u32 s38, s38, 0x80
	s_addc_u32 s39, s39, 0
	s_sub_i32 s40, s40, 0x6000
	s_cmp_lt_i32 s40, 0
	s_cselect_b32 s42, 0x12000, 0
	s_add_i32 s40, s40, s42
	s_sub_i32 s41, s41, 0x6000
	s_cmp_lt_i32 s41, 0
	s_cselect_b32 s42, 0x12000, 0
	s_add_i32 s41, s41, s42
	v_subrev_u32_e32 v196, 0x6000, v185
	v_add_u32_e32 v198, 0xc000, v185
	v_min_u32_e32 v185, v196, v198
	s_add_i32 s7, s7, 1
	s_cmp_lt_u32 s7, 15
	s_waitcnt lgkmcnt(0)
	s_barrier
	s_cbranch_scc1 .Lg4_loop
	v_add_u32_e32 v190, s40, v186
	v_add_u32_e32 v191, s40, v187
	v_add_u32_e32 v250, s40, v188
	v_add_u32_e32 v251, s40, v189
	ds_read_b128 v[200:203], v190
	ds_read_b128 v[204:207], v190 offset:2048
	ds_read_b128 v[222:225], v250
	ds_read_b128 v[226:229], v250 offset:2048
	ds_read_b128 v[230:233], v250 offset:4096
	ds_read_b128 v[234:237], v250 offset:6144
	s_waitcnt lgkmcnt(3)
	v_mfma_f32_32x32x16_bf16 v[112:127], v[200:203], v[222:225], v[112:127]
	ds_read_b128 v[208:211], v191
	v_mfma_f32_32x32x16_bf16 v[48:63], v[204:207], v[222:225], v[48:63]
	ds_read_b128 v[212:215], v191 offset:2048
	s_waitcnt lgkmcnt(4)
	v_mfma_f32_32x32x16_bf16 v[96:111], v[200:203], v[226:229], v[96:111]
	ds_read_b128 v[238:241], v251
	v_mfma_f32_32x32x16_bf16 v[32:47], v[204:207], v[226:229], v[32:47]
	ds_read_b128 v[242:245], v251 offset:2048
	s_waitcnt lgkmcnt(5)
	v_mfma_f32_32x32x16_bf16 v[80:95], v[200:203], v[230:233], v[80:95]
	ds_read_b128 v[246:249], v251 offset:4096
	v_mfma_f32_32x32x16_bf16 v[16:31], v[204:207], v[230:233], v[16:31]
	ds_read_b128 v[192:195], v251 offset:6144
	s_waitcnt lgkmcnt(6)
	v_mfma_f32_32x32x16_bf16 v[64:79], v[200:203], v[234:237], v[64:79]
	v_mfma_f32_32x32x16_bf16 v[0:15], v[204:207], v[234:237], v[0:15]
	v_xad_u32 v190, v186, 64, s41
	v_xad_u32 v250, v188, 64, s41
	s_waitcnt lgkmcnt(3)
	v_mfma_f32_32x32x16_bf16 v[112:127], v[208:211], v[238:241], v[112:127]
	ds_read_b128 v[200:203], v190
	v_mfma_f32_32x32x16_bf16 v[48:63], v[212:215], v[238:241], v[48:63]
	ds_read_b128 v[204:207], v190 offset:2048
	s_waitcnt lgkmcnt(4)
	v_mfma_f32_32x32x16_bf16 v[96:111], v[208:211], v[242:245], v[96:111]
	ds_read_b128 v[222:225], v250
	v_mfma_f32_32x32x16_bf16 v[32:47], v[212:215], v[242:245], v[32:47]
	ds_read_b128 v[226:229], v250 offset:2048
	s_waitcnt lgkmcnt(5)
	v_mfma_f32_32x32x16_bf16 v[80:95], v[208:211], v[246:249], v[80:95]
	ds_read_b128 v[230:233], v250 offset:4096
	v_mfma_f32_32x32x16_bf16 v[16:31], v[212:215], v[246:249], v[16:31]
	ds_read_b128 v[234:237], v250 offset:6144
	s_waitcnt lgkmcnt(6)
	v_mfma_f32_32x32x16_bf16 v[64:79], v[208:211], v[192:195], v[64:79]
	v_mfma_f32_32x32x16_bf16 v[0:15], v[212:215], v[192:195], v[0:15]
	v_xad_u32 v191, v187, 64, s41
	v_xad_u32 v251, v189, 64, s41
	s_waitcnt lgkmcnt(3)
	v_mfma_f32_32x32x16_bf16 v[112:127], v[200:203], v[222:225], v[112:127]
	ds_read_b128 v[208:211], v191
	v_mfma_f32_32x32x16_bf16 v[48:63], v[204:207], v[222:225], v[48:63]
	ds_read_b128 v[212:215], v191 offset:2048
	s_waitcnt lgkmcnt(4)
	v_mfma_f32_32x32x16_bf16 v[96:111], v[200:203], v[226:229], v[96:111]
	ds_read_b128 v[238:241], v251
	v_mfma_f32_32x32x16_bf16 v[32:47], v[204:207], v[226:229], v[32:47]
	ds_read_b128 v[242:245], v251 offset:2048
	s_waitcnt lgkmcnt(5)
	v_mfma_f32_32x32x16_bf16 v[80:95], v[200:203], v[230:233], v[80:95]
	ds_read_b128 v[246:249], v251 offset:4096
	v_mfma_f32_32x32x16_bf16 v[16:31], v[204:207], v[230:233], v[16:31]
	ds_read_b128 v[192:195], v251 offset:6144
	s_waitcnt lgkmcnt(6)
	v_mfma_f32_32x32x16_bf16 v[64:79], v[200:203], v[234:237], v[64:79]
	v_mfma_f32_32x32x16_bf16 v[0:15], v[204:207], v[234:237], v[0:15]
	s_waitcnt lgkmcnt(3)
	v_mfma_f32_32x32x16_bf16 v[112:127], v[208:211], v[238:241], v[112:127]
	v_mfma_f32_32x32x16_bf16 v[48:63], v[212:215], v[238:241], v[48:63]
	s_waitcnt lgkmcnt(2)
	v_mfma_f32_32x32x16_bf16 v[96:111], v[208:211], v[242:245], v[96:111]
	v_mfma_f32_32x32x16_bf16 v[32:47], v[212:215], v[242:245], v[32:47]
	s_waitcnt lgkmcnt(1)
	v_mfma_f32_32x32x16_bf16 v[80:95], v[208:211], v[246:249], v[80:95]
	v_mfma_f32_32x32x16_bf16 v[16:31], v[212:215], v[246:249], v[16:31]
	s_waitcnt lgkmcnt(0)
	v_mfma_f32_32x32x16_bf16 v[64:79], v[208:211], v[192:195], v[64:79]
	v_mfma_f32_32x32x16_bf16 v[0:15], v[212:215], v[192:195], v[0:15]
	s_setprio 0
	s_nop 7
	s_nop 7
	.p2align 6
	s_nop 0
	s_nop 0
	s_nop 0
	s_nop 0
	s_nop 0
	s_nop 0
	s_nop 0
	s_nop 0
	s_nop 0

.LBB0_482:
	s_ashr_i32 s1, s5, 7
	s_lshl_b32 s7, s1, 8
	v_bfe_u32 v128, v197, 5, 1
	v_lshl_add_u32 v129, v128, 4, s7
	v_add_u32_e32 v129, 0x12000, v129
	ds_read_b128 v[132:135], v129
	ds_read_b128 v[136:139], v129 offset:32
	ds_read_b128 v[140:143], v129 offset:64
	ds_read_b128 v[144:147], v129 offset:96
	ds_read_b128 v[148:151], v129 offset:128
	ds_read_b128 v[152:155], v129 offset:160
	ds_read_b128 v[156:159], v129 offset:192
	ds_read_b128 v[160:163], v129 offset:224
	s_lshl_b32 s7, s0, 13
	s_lshl_b32 s36, s6, 1
	s_add_u32 s7, s7, s36
	s_add_u32 s42, s70, s7
	s_addc_u32 s43, s71, 0
	s_mov_b32 s44, 0x05040100
	s_mov_b32 s45, 0x07060302
	s_lshl_b32 s36, s5, 2
	s_and_b32 s36, s36, 0x100
	v_and_b32_e32 v130, 15, v197
	v_lshlrev_b32_e32 v130, 2, v130
	v_add_u32_e32 v130, s36, v130
	v_bfe_u32 v131, v197, 4, 1
	v_lshlrev_b32_e32 v131, 1, v131
	v_lshl_add_u32 v131, v128, 2, v131
	s_lshl_b32 s37, s1, 6
	v_add_u32_e32 v131, s37, v131
	v_lshl_add_u32 v164, v131, 13, v130
	v_add_u32_e32 v165, 0x2000, v164
	s_waitcnt lgkmcnt(0)
	v_mul_f32_e32 v112, v112, v132
	v_mul_f32_e32 v113, v113, v133
	v_mul_f32_e32 v114, v114, v134
	v_mul_f32_e32 v115, v115, v135
	v_mul_f32_e32 v96, v96, v132
	v_mul_f32_e32 v97, v97, v133
	v_mul_f32_e32 v98, v98, v134
	v_mul_f32_e32 v99, v99, v135
	v_mul_f32_e32 v80, v80, v132
	v_mul_f32_e32 v81, v81, v133
	v_mul_f32_e32 v82, v82, v134
	v_mul_f32_e32 v83, v83, v135
	v_mul_f32_e32 v64, v64, v132
	v_mul_f32_e32 v65, v65, v133
	v_mul_f32_e32 v66, v66, v134
	v_mul_f32_e32 v67, v67, v135
	v_max_f32_e32 v112, 0, v112
	v_max_f32_e32 v113, 0, v113
	v_max_f32_e32 v114, 0, v114
	v_max_f32_e32 v115, 0, v115
	v_max_f32_e32 v96, 0, v96
	v_max_f32_e32 v97, 0, v97
	v_max_f32_e32 v98, 0, v98
	v_max_f32_e32 v99, 0, v99
	v_max_f32_e32 v80, 0, v80
	v_max_f32_e32 v81, 0, v81
	v_max_f32_e32 v82, 0, v82
	v_max_f32_e32 v83, 0, v83
	v_max_f32_e32 v64, 0, v64
	v_max_f32_e32 v65, 0, v65
	v_max_f32_e32 v66, 0, v66
	v_max_f32_e32 v67, 0, v67
	v_mul_f32_e32 v112, v112, v112
	v_mul_f32_e32 v113, v113, v113
	v_mul_f32_e32 v114, v114, v114
	v_mul_f32_e32 v115, v115, v115
	v_mul_f32_e32 v96, v96, v96
	v_mul_f32_e32 v97, v97, v97
	v_mul_f32_e32 v98, v98, v98
	v_mul_f32_e32 v99, v99, v99
	v_mul_f32_e32 v80, v80, v80
	v_mul_f32_e32 v81, v81, v81
	v_mul_f32_e32 v82, v82, v82
	v_mul_f32_e32 v83, v83, v83
	v_mul_f32_e32 v64, v64, v64
	v_mul_f32_e32 v65, v65, v65
	v_mul_f32_e32 v66, v66, v66
	v_mul_f32_e32 v67, v67, v67
	v_cvt_pk_bf16_f32 v112, v112, v113
	v_cvt_pk_bf16_f32 v114, v114, v115
	v_cvt_pk_bf16_f32 v96, v96, v97
	v_cvt_pk_bf16_f32 v98, v98, v99
	v_cvt_pk_bf16_f32 v80, v80, v81
	v_cvt_pk_bf16_f32 v82, v82, v83
	v_cvt_pk_bf16_f32 v64, v64, v65
	v_cvt_pk_bf16_f32 v66, v66, v67
	s_nop 1
	v_permlane16_swap_b32 v112, v114
	v_permlane16_swap_b32 v96, v98
	v_permlane16_swap_b32 v80, v82
	v_permlane16_swap_b32 v64, v66
	s_nop 0
	v_perm_b32 v113, v114, v112, s44
	v_perm_b32 v115, v114, v112, s45
	v_perm_b32 v97, v98, v96, s44
	v_perm_b32 v99, v98, v96, s45
	v_perm_b32 v81, v82, v80, s44
	v_perm_b32 v83, v82, v80, s45
	v_perm_b32 v65, v66, v64, s44
	v_perm_b32 v67, v66, v64, s45
	global_store_dword v164, v113, s[42:43]
	global_store_dword v165, v115, s[42:43]
	global_store_dword v164, v97, s[42:43] offset:64
	global_store_dword v165, v99, s[42:43] offset:64
	global_store_dword v164, v81, s[42:43] offset:128
	global_store_dword v165, v83, s[42:43] offset:128
	global_store_dword v164, v65, s[42:43] offset:192
	global_store_dword v165, v67, s[42:43] offset:192
	v_add_u32_e32 v164, 0x10000, v164
	v_add_u32_e32 v165, 0x10000, v165
	v_mul_f32_e32 v116, v116, v136
	v_mul_f32_e32 v117, v117, v137
	v_mul_f32_e32 v118, v118, v138
	v_mul_f32_e32 v119, v119, v139
	v_mul_f32_e32 v100, v100, v136
	v_mul_f32_e32 v101, v101, v137
	v_mul_f32_e32 v102, v102, v138
	v_mul_f32_e32 v103, v103, v139
	v_mul_f32_e32 v84, v84, v136
	v_mul_f32_e32 v85, v85, v137
	v_mul_f32_e32 v86, v86, v138
	v_mul_f32_e32 v87, v87, v139
	v_mul_f32_e32 v68, v68, v136
	v_mul_f32_e32 v69, v69, v137
	v_mul_f32_e32 v70, v70, v138
	v_mul_f32_e32 v71, v71, v139
	v_max_f32_e32 v116, 0, v116
	v_max_f32_e32 v117, 0, v117
	v_max_f32_e32 v118, 0, v118
	v_max_f32_e32 v119, 0, v119
	v_max_f32_e32 v100, 0, v100
	v_max_f32_e32 v101, 0, v101
	v_max_f32_e32 v102, 0, v102
	v_max_f32_e32 v103, 0, v103
	v_max_f32_e32 v84, 0, v84
	v_max_f32_e32 v85, 0, v85
	v_max_f32_e32 v86, 0, v86
	v_max_f32_e32 v87, 0, v87
	v_max_f32_e32 v68, 0, v68
	v_max_f32_e32 v69, 0, v69
	v_max_f32_e32 v70, 0, v70
	v_max_f32_e32 v71, 0, v71
	v_mul_f32_e32 v116, v116, v116
	v_mul_f32_e32 v117, v117, v117
	v_mul_f32_e32 v118, v118, v118
	v_mul_f32_e32 v119, v119, v119
	v_mul_f32_e32 v100, v100, v100
	v_mul_f32_e32 v101, v101, v101
	v_mul_f32_e32 v102, v102, v102
	v_mul_f32_e32 v103, v103, v103
	v_mul_f32_e32 v84, v84, v84
	v_mul_f32_e32 v85, v85, v85
	v_mul_f32_e32 v86, v86, v86
	v_mul_f32_e32 v87, v87, v87
	v_mul_f32_e32 v68, v68, v68
	v_mul_f32_e32 v69, v69, v69
	v_mul_f32_e32 v70, v70, v70
	v_mul_f32_e32 v71, v71, v71
	v_cvt_pk_bf16_f32 v116, v116, v117
	v_cvt_pk_bf16_f32 v118, v118, v119
	v_cvt_pk_bf16_f32 v100, v100, v101
	v_cvt_pk_bf16_f32 v102, v102, v103
	v_cvt_pk_bf16_f32 v84, v84, v85
	v_cvt_pk_bf16_f32 v86, v86, v87
	v_cvt_pk_bf16_f32 v68, v68, v69
	v_cvt_pk_bf16_f32 v70, v70, v71
	s_nop 1
	v_permlane16_swap_b32 v116, v118
	v_permlane16_swap_b32 v100, v102
	v_permlane16_swap_b32 v84, v86
	v_permlane16_swap_b32 v68, v70
	s_nop 0
	v_perm_b32 v117, v118, v116, s44
	v_perm_b32 v119, v118, v116, s45
	v_perm_b32 v101, v102, v100, s44
	v_perm_b32 v103, v102, v100, s45
	v_perm_b32 v85, v86, v84, s44
	v_perm_b32 v87, v86, v84, s45
	v_perm_b32 v69, v70, v68, s44
	v_perm_b32 v71, v70, v68, s45
	global_store_dword v164, v117, s[42:43]
	global_store_dword v165, v119, s[42:43]
	global_store_dword v164, v101, s[42:43] offset:64
	global_store_dword v165, v103, s[42:43] offset:64
	global_store_dword v164, v85, s[42:43] offset:128
	global_store_dword v165, v87, s[42:43] offset:128
	global_store_dword v164, v69, s[42:43] offset:192
	global_store_dword v165, v71, s[42:43] offset:192
	v_add_u32_e32 v164, 0x10000, v164
	v_add_u32_e32 v165, 0x10000, v165
	v_mul_f32_e32 v120, v120, v140
	v_mul_f32_e32 v121, v121, v141
	v_mul_f32_e32 v122, v122, v142
	v_mul_f32_e32 v123, v123, v143
	v_mul_f32_e32 v104, v104, v140
	v_mul_f32_e32 v105, v105, v141
	v_mul_f32_e32 v106, v106, v142
	v_mul_f32_e32 v107, v107, v143
	v_mul_f32_e32 v88, v88, v140
	v_mul_f32_e32 v89, v89, v141
	v_mul_f32_e32 v90, v90, v142
	v_mul_f32_e32 v91, v91, v143
	v_mul_f32_e32 v72, v72, v140
	v_mul_f32_e32 v73, v73, v141
	v_mul_f32_e32 v74, v74, v142
	v_mul_f32_e32 v75, v75, v143
	v_max_f32_e32 v120, 0, v120
	v_max_f32_e32 v121, 0, v121
	v_max_f32_e32 v122, 0, v122
	v_max_f32_e32 v123, 0, v123
	v_max_f32_e32 v104, 0, v104
	v_max_f32_e32 v105, 0, v105
	v_max_f32_e32 v106, 0, v106
	v_max_f32_e32 v107, 0, v107
	v_max_f32_e32 v88, 0, v88
	v_max_f32_e32 v89, 0, v89
	v_max_f32_e32 v90, 0, v90
	v_max_f32_e32 v91, 0, v91
	v_max_f32_e32 v72, 0, v72
	v_max_f32_e32 v73, 0, v73
	v_max_f32_e32 v74, 0, v74
	v_max_f32_e32 v75, 0, v75
	v_mul_f32_e32 v120, v120, v120
	v_mul_f32_e32 v121, v121, v121
	v_mul_f32_e32 v122, v122, v122
	v_mul_f32_e32 v123, v123, v123
	v_mul_f32_e32 v104, v104, v104
	v_mul_f32_e32 v105, v105, v105
	v_mul_f32_e32 v106, v106, v106
	v_mul_f32_e32 v107, v107, v107
	v_mul_f32_e32 v88, v88, v88
	v_mul_f32_e32 v89, v89, v89
	v_mul_f32_e32 v90, v90, v90
	v_mul_f32_e32 v91, v91, v91
	v_mul_f32_e32 v72, v72, v72
	v_mul_f32_e32 v73, v73, v73
	v_mul_f32_e32 v74, v74, v74
	v_mul_f32_e32 v75, v75, v75
	v_cvt_pk_bf16_f32 v120, v120, v121
	v_cvt_pk_bf16_f32 v122, v122, v123
	v_cvt_pk_bf16_f32 v104, v104, v105
	v_cvt_pk_bf16_f32 v106, v106, v107
	v_cvt_pk_bf16_f32 v88, v88, v89
	v_cvt_pk_bf16_f32 v90, v90, v91
	v_cvt_pk_bf16_f32 v72, v72, v73
	v_cvt_pk_bf16_f32 v74, v74, v75
	s_nop 1
	v_permlane16_swap_b32 v120, v122
	v_permlane16_swap_b32 v104, v106
	v_permlane16_swap_b32 v88, v90
	v_permlane16_swap_b32 v72, v74
	s_nop 0
	v_perm_b32 v121, v122, v120, s44
	v_perm_b32 v123, v122, v120, s45
	v_perm_b32 v105, v106, v104, s44
	v_perm_b32 v107, v106, v104, s45
	v_perm_b32 v89, v90, v88, s44
	v_perm_b32 v91, v90, v88, s45
	v_perm_b32 v73, v74, v72, s44
	v_perm_b32 v75, v74, v72, s45
	global_store_dword v164, v121, s[42:43]
	global_store_dword v165, v123, s[42:43]
	global_store_dword v164, v105, s[42:43] offset:64
	global_store_dword v165, v107, s[42:43] offset:64
	global_store_dword v164, v89, s[42:43] offset:128
	global_store_dword v165, v91, s[42:43] offset:128
	global_store_dword v164, v73, s[42:43] offset:192
	global_store_dword v165, v75, s[42:43] offset:192
	v_add_u32_e32 v164, 0x10000, v164
	v_add_u32_e32 v165, 0x10000, v165
	v_mul_f32_e32 v124, v124, v144
	v_mul_f32_e32 v125, v125, v145
	v_mul_f32_e32 v126, v126, v146
	v_mul_f32_e32 v127, v127, v147
	v_mul_f32_e32 v108, v108, v144
	v_mul_f32_e32 v109, v109, v145
	v_mul_f32_e32 v110, v110, v146
	v_mul_f32_e32 v111, v111, v147
	v_mul_f32_e32 v92, v92, v144
	v_mul_f32_e32 v93, v93, v145
	v_mul_f32_e32 v94, v94, v146
	v_mul_f32_e32 v95, v95, v147
	v_mul_f32_e32 v76, v76, v144
	v_mul_f32_e32 v77, v77, v145
	v_mul_f32_e32 v78, v78, v146
	v_mul_f32_e32 v79, v79, v147
	v_max_f32_e32 v124, 0, v124
	v_max_f32_e32 v125, 0, v125
	v_max_f32_e32 v126, 0, v126
	v_max_f32_e32 v127, 0, v127
	v_max_f32_e32 v108, 0, v108
	v_max_f32_e32 v109, 0, v109
	v_max_f32_e32 v110, 0, v110
	v_max_f32_e32 v111, 0, v111
	v_max_f32_e32 v92, 0, v92
	v_max_f32_e32 v93, 0, v93
	v_max_f32_e32 v94, 0, v94
	v_max_f32_e32 v95, 0, v95
	v_max_f32_e32 v76, 0, v76
	v_max_f32_e32 v77, 0, v77
	v_max_f32_e32 v78, 0, v78
	v_max_f32_e32 v79, 0, v79
	v_mul_f32_e32 v124, v124, v124
	v_mul_f32_e32 v125, v125, v125
	v_mul_f32_e32 v126, v126, v126
	v_mul_f32_e32 v127, v127, v127
	v_mul_f32_e32 v108, v108, v108
	v_mul_f32_e32 v109, v109, v109
	v_mul_f32_e32 v110, v110, v110
	v_mul_f32_e32 v111, v111, v111
	v_mul_f32_e32 v92, v92, v92
	v_mul_f32_e32 v93, v93, v93
	v_mul_f32_e32 v94, v94, v94
	v_mul_f32_e32 v95, v95, v95
	v_mul_f32_e32 v76, v76, v76
	v_mul_f32_e32 v77, v77, v77
	v_mul_f32_e32 v78, v78, v78
	v_mul_f32_e32 v79, v79, v79
	v_cvt_pk_bf16_f32 v124, v124, v125
	v_cvt_pk_bf16_f32 v126, v126, v127
	v_cvt_pk_bf16_f32 v108, v108, v109
	v_cvt_pk_bf16_f32 v110, v110, v111
	v_cvt_pk_bf16_f32 v92, v92, v93
	v_cvt_pk_bf16_f32 v94, v94, v95
	v_cvt_pk_bf16_f32 v76, v76, v77
	v_cvt_pk_bf16_f32 v78, v78, v79
	s_nop 1
	v_permlane16_swap_b32 v124, v126
	v_permlane16_swap_b32 v108, v110
	v_permlane16_swap_b32 v92, v94
	v_permlane16_swap_b32 v76, v78
	s_nop 0
	v_perm_b32 v125, v126, v124, s44
	v_perm_b32 v127, v126, v124, s45
	v_perm_b32 v109, v110, v108, s44
	v_perm_b32 v111, v110, v108, s45
	v_perm_b32 v93, v94, v92, s44
	v_perm_b32 v95, v94, v92, s45
	v_perm_b32 v77, v78, v76, s44
	v_perm_b32 v79, v78, v76, s45
	global_store_dword v164, v125, s[42:43]
	global_store_dword v165, v127, s[42:43]
	global_store_dword v164, v109, s[42:43] offset:64
	global_store_dword v165, v111, s[42:43] offset:64
	global_store_dword v164, v93, s[42:43] offset:128
	global_store_dword v165, v95, s[42:43] offset:128
	global_store_dword v164, v77, s[42:43] offset:192
	global_store_dword v165, v79, s[42:43] offset:192
	v_add_u32_e32 v164, 0x10000, v164
	v_add_u32_e32 v165, 0x10000, v165
	v_mul_f32_e32 v48, v48, v148
	v_mul_f32_e32 v49, v49, v149
	v_mul_f32_e32 v50, v50, v150
	v_mul_f32_e32 v51, v51, v151
	v_mul_f32_e32 v32, v32, v148
	v_mul_f32_e32 v33, v33, v149
	v_mul_f32_e32 v34, v34, v150
	v_mul_f32_e32 v35, v35, v151
	v_mul_f32_e32 v16, v16, v148
	v_mul_f32_e32 v17, v17, v149
	v_mul_f32_e32 v18, v18, v150
	v_mul_f32_e32 v19, v19, v151
	v_mul_f32_e32 v0, v0, v148
	v_mul_f32_e32 v1, v1, v149
	v_mul_f32_e32 v2, v2, v150
	v_mul_f32_e32 v3, v3, v151
	v_max_f32_e32 v48, 0, v48
	v_max_f32_e32 v49, 0, v49
	v_max_f32_e32 v50, 0, v50
	v_max_f32_e32 v51, 0, v51
	v_max_f32_e32 v32, 0, v32
	v_max_f32_e32 v33, 0, v33
	v_max_f32_e32 v34, 0, v34
	v_max_f32_e32 v35, 0, v35
	v_max_f32_e32 v16, 0, v16
	v_max_f32_e32 v17, 0, v17
	v_max_f32_e32 v18, 0, v18
	v_max_f32_e32 v19, 0, v19
	v_max_f32_e32 v0, 0, v0
	v_max_f32_e32 v1, 0, v1
	v_max_f32_e32 v2, 0, v2
	v_max_f32_e32 v3, 0, v3
	v_mul_f32_e32 v48, v48, v48
	v_mul_f32_e32 v49, v49, v49
	v_mul_f32_e32 v50, v50, v50
	v_mul_f32_e32 v51, v51, v51
	v_mul_f32_e32 v32, v32, v32
	v_mul_f32_e32 v33, v33, v33
	v_mul_f32_e32 v34, v34, v34
	v_mul_f32_e32 v35, v35, v35
	v_mul_f32_e32 v16, v16, v16
	v_mul_f32_e32 v17, v17, v17
	v_mul_f32_e32 v18, v18, v18
	v_mul_f32_e32 v19, v19, v19
	v_mul_f32_e32 v0, v0, v0
	v_mul_f32_e32 v1, v1, v1
	v_mul_f32_e32 v2, v2, v2
	v_mul_f32_e32 v3, v3, v3
	v_cvt_pk_bf16_f32 v48, v48, v49
	v_cvt_pk_bf16_f32 v50, v50, v51
	v_cvt_pk_bf16_f32 v32, v32, v33
	v_cvt_pk_bf16_f32 v34, v34, v35
	v_cvt_pk_bf16_f32 v16, v16, v17
	v_cvt_pk_bf16_f32 v18, v18, v19
	v_cvt_pk_bf16_f32 v0, v0, v1
	v_cvt_pk_bf16_f32 v2, v2, v3
	s_nop 1
	v_permlane16_swap_b32 v48, v50
	v_permlane16_swap_b32 v32, v34
	v_permlane16_swap_b32 v16, v18
	v_permlane16_swap_b32 v0, v2
	s_nop 0
	v_perm_b32 v49, v50, v48, s44
	v_perm_b32 v51, v50, v48, s45
	v_perm_b32 v33, v34, v32, s44
	v_perm_b32 v35, v34, v32, s45
	v_perm_b32 v17, v18, v16, s44
	v_perm_b32 v19, v18, v16, s45
	v_perm_b32 v1, v2, v0, s44
	v_perm_b32 v3, v2, v0, s45
	global_store_dword v164, v49, s[42:43]
	global_store_dword v165, v51, s[42:43]
	global_store_dword v164, v33, s[42:43] offset:64
	global_store_dword v165, v35, s[42:43] offset:64
	global_store_dword v164, v17, s[42:43] offset:128
	global_store_dword v165, v19, s[42:43] offset:128
	global_store_dword v164, v1, s[42:43] offset:192
	global_store_dword v165, v3, s[42:43] offset:192
	v_add_u32_e32 v164, 0x10000, v164
	v_add_u32_e32 v165, 0x10000, v165
	v_mul_f32_e32 v52, v52, v152
	v_mul_f32_e32 v53, v53, v153
	v_mul_f32_e32 v54, v54, v154
	v_mul_f32_e32 v55, v55, v155
	v_mul_f32_e32 v36, v36, v152
	v_mul_f32_e32 v37, v37, v153
	v_mul_f32_e32 v38, v38, v154
	v_mul_f32_e32 v39, v39, v155
	v_mul_f32_e32 v20, v20, v152
	v_mul_f32_e32 v21, v21, v153
	v_mul_f32_e32 v22, v22, v154
	v_mul_f32_e32 v23, v23, v155
	v_mul_f32_e32 v4, v4, v152
	v_mul_f32_e32 v5, v5, v153
	v_mul_f32_e32 v6, v6, v154
	v_mul_f32_e32 v7, v7, v155
	v_max_f32_e32 v52, 0, v52
	v_max_f32_e32 v53, 0, v53
	v_max_f32_e32 v54, 0, v54
	v_max_f32_e32 v55, 0, v55
	v_max_f32_e32 v36, 0, v36
	v_max_f32_e32 v37, 0, v37
	v_max_f32_e32 v38, 0, v38
	v_max_f32_e32 v39, 0, v39
	v_max_f32_e32 v20, 0, v20
	v_max_f32_e32 v21, 0, v21
	v_max_f32_e32 v22, 0, v22
	v_max_f32_e32 v23, 0, v23
	v_max_f32_e32 v4, 0, v4
	v_max_f32_e32 v5, 0, v5
	v_max_f32_e32 v6, 0, v6
	v_max_f32_e32 v7, 0, v7
	v_mul_f32_e32 v52, v52, v52
	v_mul_f32_e32 v53, v53, v53
	v_mul_f32_e32 v54, v54, v54
	v_mul_f32_e32 v55, v55, v55
	v_mul_f32_e32 v36, v36, v36
	v_mul_f32_e32 v37, v37, v37
	v_mul_f32_e32 v38, v38, v38
	v_mul_f32_e32 v39, v39, v39
	v_mul_f32_e32 v20, v20, v20
	v_mul_f32_e32 v21, v21, v21
	v_mul_f32_e32 v22, v22, v22
	v_mul_f32_e32 v23, v23, v23
	v_mul_f32_e32 v4, v4, v4
	v_mul_f32_e32 v5, v5, v5
	v_mul_f32_e32 v6, v6, v6
	v_mul_f32_e32 v7, v7, v7
	v_cvt_pk_bf16_f32 v52, v52, v53
	v_cvt_pk_bf16_f32 v54, v54, v55
	v_cvt_pk_bf16_f32 v36, v36, v37
	v_cvt_pk_bf16_f32 v38, v38, v39
	v_cvt_pk_bf16_f32 v20, v20, v21
	v_cvt_pk_bf16_f32 v22, v22, v23
	v_cvt_pk_bf16_f32 v4, v4, v5
	v_cvt_pk_bf16_f32 v6, v6, v7
	s_nop 1
	v_permlane16_swap_b32 v52, v54
	v_permlane16_swap_b32 v36, v38
	v_permlane16_swap_b32 v20, v22
	v_permlane16_swap_b32 v4, v6
	s_nop 0
	v_perm_b32 v53, v54, v52, s44
	v_perm_b32 v55, v54, v52, s45
	v_perm_b32 v37, v38, v36, s44
	v_perm_b32 v39, v38, v36, s45
	v_perm_b32 v21, v22, v20, s44
	v_perm_b32 v23, v22, v20, s45
	v_perm_b32 v5, v6, v4, s44
	v_perm_b32 v7, v6, v4, s45
	global_store_dword v164, v53, s[42:43]
	global_store_dword v165, v55, s[42:43]
	global_store_dword v164, v37, s[42:43] offset:64
	global_store_dword v165, v39, s[42:43] offset:64
	global_store_dword v164, v21, s[42:43] offset:128
	global_store_dword v165, v23, s[42:43] offset:128
	global_store_dword v164, v5, s[42:43] offset:192
	global_store_dword v165, v7, s[42:43] offset:192
	v_add_u32_e32 v164, 0x10000, v164
	v_add_u32_e32 v165, 0x10000, v165
	v_mul_f32_e32 v56, v56, v156
	v_mul_f32_e32 v57, v57, v157
	v_mul_f32_e32 v58, v58, v158
	v_mul_f32_e32 v59, v59, v159
	v_mul_f32_e32 v40, v40, v156
	v_mul_f32_e32 v41, v41, v157
	v_mul_f32_e32 v42, v42, v158
	v_mul_f32_e32 v43, v43, v159
	v_mul_f32_e32 v24, v24, v156
	v_mul_f32_e32 v25, v25, v157
	v_mul_f32_e32 v26, v26, v158
	v_mul_f32_e32 v27, v27, v159
	v_mul_f32_e32 v8, v8, v156
	v_mul_f32_e32 v9, v9, v157
	v_mul_f32_e32 v10, v10, v158
	v_mul_f32_e32 v11, v11, v159
	v_max_f32_e32 v56, 0, v56
	v_max_f32_e32 v57, 0, v57
	v_max_f32_e32 v58, 0, v58
	v_max_f32_e32 v59, 0, v59
	v_max_f32_e32 v40, 0, v40
	v_max_f32_e32 v41, 0, v41
	v_max_f32_e32 v42, 0, v42
	v_max_f32_e32 v43, 0, v43
	v_max_f32_e32 v24, 0, v24
	v_max_f32_e32 v25, 0, v25
	v_max_f32_e32 v26, 0, v26
	v_max_f32_e32 v27, 0, v27
	v_max_f32_e32 v8, 0, v8
	v_max_f32_e32 v9, 0, v9
	v_max_f32_e32 v10, 0, v10
	v_max_f32_e32 v11, 0, v11
	v_mul_f32_e32 v56, v56, v56
	v_mul_f32_e32 v57, v57, v57
	v_mul_f32_e32 v58, v58, v58
	v_mul_f32_e32 v59, v59, v59
	v_mul_f32_e32 v40, v40, v40
	v_mul_f32_e32 v41, v41, v41
	v_mul_f32_e32 v42, v42, v42
	v_mul_f32_e32 v43, v43, v43
	v_mul_f32_e32 v24, v24, v24
	v_mul_f32_e32 v25, v25, v25
	v_mul_f32_e32 v26, v26, v26
	v_mul_f32_e32 v27, v27, v27
	v_mul_f32_e32 v8, v8, v8
	v_mul_f32_e32 v9, v9, v9
	v_mul_f32_e32 v10, v10, v10
	v_mul_f32_e32 v11, v11, v11
	v_cvt_pk_bf16_f32 v56, v56, v57
	v_cvt_pk_bf16_f32 v58, v58, v59
	v_cvt_pk_bf16_f32 v40, v40, v41
	v_cvt_pk_bf16_f32 v42, v42, v43
	v_cvt_pk_bf16_f32 v24, v24, v25
	v_cvt_pk_bf16_f32 v26, v26, v27
	v_cvt_pk_bf16_f32 v8, v8, v9
	v_cvt_pk_bf16_f32 v10, v10, v11
	s_nop 1
	v_permlane16_swap_b32 v56, v58
	v_permlane16_swap_b32 v40, v42
	v_permlane16_swap_b32 v24, v26
	v_permlane16_swap_b32 v8, v10
	s_nop 0
	v_perm_b32 v57, v58, v56, s44
	v_perm_b32 v59, v58, v56, s45
	v_perm_b32 v41, v42, v40, s44
	v_perm_b32 v43, v42, v40, s45
	v_perm_b32 v25, v26, v24, s44
	v_perm_b32 v27, v26, v24, s45
	v_perm_b32 v9, v10, v8, s44
	v_perm_b32 v11, v10, v8, s45
	global_store_dword v164, v57, s[42:43]
	global_store_dword v165, v59, s[42:43]
	global_store_dword v164, v41, s[42:43] offset:64
	global_store_dword v165, v43, s[42:43] offset:64
	global_store_dword v164, v25, s[42:43] offset:128
	global_store_dword v165, v27, s[42:43] offset:128
	global_store_dword v164, v9, s[42:43] offset:192
	global_store_dword v165, v11, s[42:43] offset:192
	v_add_u32_e32 v164, 0x10000, v164
	v_add_u32_e32 v165, 0x10000, v165
	v_mul_f32_e32 v60, v60, v160
	v_mul_f32_e32 v61, v61, v161
	v_mul_f32_e32 v62, v62, v162
	v_mul_f32_e32 v63, v63, v163
	v_mul_f32_e32 v44, v44, v160
	v_mul_f32_e32 v45, v45, v161
	v_mul_f32_e32 v46, v46, v162
	v_mul_f32_e32 v47, v47, v163
	v_mul_f32_e32 v28, v28, v160
	v_mul_f32_e32 v29, v29, v161
	v_mul_f32_e32 v30, v30, v162
	v_mul_f32_e32 v31, v31, v163
	v_mul_f32_e32 v12, v12, v160
	v_mul_f32_e32 v13, v13, v161
	v_mul_f32_e32 v14, v14, v162
	v_mul_f32_e32 v15, v15, v163
	v_max_f32_e32 v60, 0, v60
	v_max_f32_e32 v61, 0, v61
	v_max_f32_e32 v62, 0, v62
	v_max_f32_e32 v63, 0, v63
	v_max_f32_e32 v44, 0, v44
	v_max_f32_e32 v45, 0, v45
	v_max_f32_e32 v46, 0, v46
	v_max_f32_e32 v47, 0, v47
	v_max_f32_e32 v28, 0, v28
	v_max_f32_e32 v29, 0, v29
	v_max_f32_e32 v30, 0, v30
	v_max_f32_e32 v31, 0, v31
	v_max_f32_e32 v12, 0, v12
	v_max_f32_e32 v13, 0, v13
	v_max_f32_e32 v14, 0, v14
	v_max_f32_e32 v15, 0, v15
	v_mul_f32_e32 v60, v60, v60
	v_mul_f32_e32 v61, v61, v61
	v_mul_f32_e32 v62, v62, v62
	v_mul_f32_e32 v63, v63, v63
	v_mul_f32_e32 v44, v44, v44
	v_mul_f32_e32 v45, v45, v45
	v_mul_f32_e32 v46, v46, v46
	v_mul_f32_e32 v47, v47, v47
	v_mul_f32_e32 v28, v28, v28
	v_mul_f32_e32 v29, v29, v29
	v_mul_f32_e32 v30, v30, v30
	v_mul_f32_e32 v31, v31, v31
	v_mul_f32_e32 v12, v12, v12
	v_mul_f32_e32 v13, v13, v13
	v_mul_f32_e32 v14, v14, v14
	v_mul_f32_e32 v15, v15, v15
	v_cvt_pk_bf16_f32 v60, v60, v61
	v_cvt_pk_bf16_f32 v62, v62, v63
	v_cvt_pk_bf16_f32 v44, v44, v45
	v_cvt_pk_bf16_f32 v46, v46, v47
	v_cvt_pk_bf16_f32 v28, v28, v29
	v_cvt_pk_bf16_f32 v30, v30, v31
	v_cvt_pk_bf16_f32 v12, v12, v13
	v_cvt_pk_bf16_f32 v14, v14, v15
	s_nop 1
	v_permlane16_swap_b32 v60, v62
	v_permlane16_swap_b32 v44, v46
	v_permlane16_swap_b32 v28, v30
	v_permlane16_swap_b32 v12, v14
	s_nop 0
	v_perm_b32 v61, v62, v60, s44
	v_perm_b32 v63, v62, v60, s45
	v_perm_b32 v45, v46, v44, s44
	v_perm_b32 v47, v46, v44, s45
	v_perm_b32 v29, v30, v28, s44
	v_perm_b32 v31, v30, v28, s45
	v_perm_b32 v13, v14, v12, s44
	v_perm_b32 v15, v14, v12, s45
	global_store_dword v164, v61, s[42:43]
	global_store_dword v165, v63, s[42:43]
	global_store_dword v164, v45, s[42:43] offset:64
	global_store_dword v165, v47, s[42:43] offset:64
	global_store_dword v164, v29, s[42:43] offset:128
	global_store_dword v165, v31, s[42:43] offset:128
	global_store_dword v164, v13, s[42:43] offset:192
	global_store_dword v165, v15, s[42:43] offset:192
	s_add_i32 s4, s4, s90
	s_cmpk_gt_i32 s4, 0x7ff
	s_barrier
	s_cbranch_scc1 .LBB0_496
	.p2align 6
	s_nop 0
	s_nop 0
	s_nop 0
	s_nop 0
	s_nop 0
	s_nop 0
	s_nop 0
	s_nop 0
	s_nop 0
	s_nop 0
	s_nop 0
	s_nop 0
	s_nop 0
	s_nop 0
	s_nop 0

.Lg5_noraise:
.Lg5_loop:
	v_add_u32_e32 v190, s36, v186
	v_add_u32_e32 v191, s36, v187
	v_add_u32_e32 v250, s36, v188
	v_add_u32_e32 v251, s36, v189
	ds_read_b128 v[200:203], v190
	ds_read_b128 v[204:207], v190 offset:2048
	ds_read_b128 v[222:225], v250
	ds_read_b128 v[226:229], v250 offset:2048
	ds_read_b128 v[230:233], v250 offset:4096
	ds_read_b128 v[234:237], v250 offset:6144
	s_waitcnt lgkmcnt(3)
	v_mfma_f32_32x32x16_bf16 v[112:127], v[200:203], v[222:225], v[112:127]
	global_load_dwordx4 v[128:131], v178, s[42:43]
	ds_read_b128 v[208:211], v191
	v_mfma_f32_32x32x16_bf16 v[48:63], v[204:207], v[222:225], v[48:63]
	global_load_dwordx4 v[132:135], v179, s[42:43]
	ds_read_b128 v[212:215], v191 offset:2048
	s_waitcnt lgkmcnt(4)
	v_mfma_f32_32x32x16_bf16 v[96:111], v[200:203], v[226:229], v[96:111]
	global_load_dwordx4 v[136:139], v180, s[42:43]
	ds_read_b128 v[238:241], v251
	v_mfma_f32_32x32x16_bf16 v[32:47], v[204:207], v[226:229], v[32:47]
	global_load_dwordx4 v[140:143], v181, s[42:43]
	ds_read_b128 v[242:245], v251 offset:2048
	s_waitcnt lgkmcnt(5)
	v_mfma_f32_32x32x16_bf16 v[80:95], v[200:203], v[230:233], v[80:95]
	global_load_dwordx4 v[144:147], v176, s[44:45]
	ds_read_b128 v[246:249], v251 offset:4096
	v_mfma_f32_32x32x16_bf16 v[16:31], v[204:207], v[230:233], v[16:31]
	global_load_dwordx4 v[148:151], v216, s[44:45]
	ds_read_b128 v[192:195], v251 offset:6144
	s_waitcnt lgkmcnt(6)
	v_mfma_f32_32x32x16_bf16 v[64:79], v[200:203], v[234:237], v[64:79]
	global_load_dwordx4 v[152:155], v217, s[44:45]
	v_mfma_f32_32x32x16_bf16 v[0:15], v[204:207], v[234:237], v[0:15]
	global_load_dwordx4 v[156:159], v218, s[44:45]
	v_xad_u32 v190, v186, 64, s37
	v_xad_u32 v250, v188, 64, s37
	s_waitcnt lgkmcnt(3)
	v_mfma_f32_32x32x16_bf16 v[112:127], v[208:211], v[238:241], v[112:127]
	global_load_dwordx4 v[160:163], v182, s[44:45]
	ds_read_b128 v[200:203], v190
	v_mfma_f32_32x32x16_bf16 v[48:63], v[212:215], v[238:241], v[48:63]
	global_load_dwordx4 v[164:167], v183, s[44:45]
	ds_read_b128 v[204:207], v190 offset:2048
	s_waitcnt lgkmcnt(4)
	v_mfma_f32_32x32x16_bf16 v[96:111], v[208:211], v[242:245], v[96:111]
	global_load_dwordx4 v[168:171], v184, s[44:45]
	ds_read_b128 v[222:225], v250
	v_mfma_f32_32x32x16_bf16 v[32:47], v[212:215], v[242:245], v[32:47]
	global_load_dwordx4 v[172:175], v185, s[44:45]
	ds_read_b128 v[226:229], v250 offset:2048
	s_waitcnt lgkmcnt(5)
	v_mfma_f32_32x32x16_bf16 v[80:95], v[208:211], v[246:249], v[80:95]
	ds_read_b128 v[230:233], v250 offset:4096
	v_mfma_f32_32x32x16_bf16 v[16:31], v[212:215], v[246:249], v[16:31]
	ds_read_b128 v[234:237], v250 offset:6144
	s_waitcnt lgkmcnt(6)
	v_mfma_f32_32x32x16_bf16 v[64:79], v[208:211], v[192:195], v[64:79]
	v_mfma_f32_32x32x16_bf16 v[0:15], v[212:215], v[192:195], v[0:15]
	s_barrier
	v_xad_u32 v191, v187, 64, s37
	v_xad_u32 v251, v189, 64, s37
	s_waitcnt lgkmcnt(3)
	v_mfma_f32_32x32x16_bf16 v[112:127], v[200:203], v[222:225], v[112:127]
	ds_read_b128 v[208:211], v191
	v_mfma_f32_32x32x16_bf16 v[48:63], v[204:207], v[222:225], v[48:63]
	ds_read_b128 v[212:215], v191 offset:2048
	s_waitcnt lgkmcnt(4)
	v_mfma_f32_32x32x16_bf16 v[96:111], v[200:203], v[226:229], v[96:111]
	ds_read_b128 v[238:241], v251
	s_waitcnt vmcnt(11)
	ds_write_b128 v177, v[128:131]
	v_mfma_f32_32x32x16_bf16 v[32:47], v[204:207], v[226:229], v[32:47]
	ds_read_b128 v[242:245], v251 offset:2048
	s_waitcnt vmcnt(10)
	ds_write_b128 v177, v[132:135] offset:2048
	s_waitcnt lgkmcnt(7)
	v_mfma_f32_32x32x16_bf16 v[80:95], v[200:203], v[230:233], v[80:95]
	ds_read_b128 v[246:249], v251 offset:4096
	s_waitcnt vmcnt(9)
	ds_write_b128 v177, v[136:139] offset:4096
	v_mfma_f32_32x32x16_bf16 v[16:31], v[204:207], v[230:233], v[16:31]
	ds_read_b128 v[192:195], v251 offset:6144
	s_waitcnt vmcnt(8)
	ds_write_b128 v177, v[140:143] offset:6144
	s_waitcnt lgkmcnt(10)
	v_mfma_f32_32x32x16_bf16 v[64:79], v[200:203], v[234:237], v[64:79]
	s_waitcnt vmcnt(7)
	ds_write_b128 v177, v[144:147] offset:8192
	v_mfma_f32_32x32x16_bf16 v[0:15], v[204:207], v[234:237], v[0:15]
	s_waitcnt vmcnt(6)
	ds_write_b128 v177, v[148:151] offset:10240
	s_waitcnt lgkmcnt(9)
	v_mfma_f32_32x32x16_bf16 v[112:127], v[208:211], v[238:241], v[112:127]
	s_waitcnt vmcnt(5)
	ds_write_b128 v177, v[152:155] offset:12288
	v_mfma_f32_32x32x16_bf16 v[48:63], v[212:215], v[238:241], v[48:63]
	s_waitcnt vmcnt(4)
	ds_write_b128 v177, v[156:159] offset:14336
	s_waitcnt lgkmcnt(9)
	v_mfma_f32_32x32x16_bf16 v[96:111], v[208:211], v[242:245], v[96:111]
	s_waitcnt vmcnt(3)
	ds_write_b128 v177, v[160:163] offset:16384
	v_mfma_f32_32x32x16_bf16 v[32:47], v[212:215], v[242:245], v[32:47]
	s_waitcnt vmcnt(2)
	ds_write_b128 v177, v[164:167] offset:18432
	s_waitcnt lgkmcnt(9)
	v_mfma_f32_32x32x16_bf16 v[80:95], v[208:211], v[246:249], v[80:95]
	s_waitcnt vmcnt(1)
	ds_write_b128 v177, v[168:171] offset:20480
	v_mfma_f32_32x32x16_bf16 v[16:31], v[212:215], v[246:249], v[16:31]
	s_waitcnt vmcnt(0)
	ds_write_b128 v177, v[172:175] offset:22528
	s_waitcnt lgkmcnt(9)
	v_mfma_f32_32x32x16_bf16 v[64:79], v[208:211], v[192:195], v[64:79]
	v_mfma_f32_32x32x16_bf16 v[0:15], v[212:215], v[192:195], v[0:15]
	s_add_u32 s42, s42, 0x80
	s_addc_u32 s43, s43, 0
	s_add_u32 s44, s44, 0x80
	s_addc_u32 s45, s45, 0
	s_sub_i32 s36, s36, 0x6000
	s_cmp_lt_i32 s36, 0
	s_cselect_b32 s38, 0x12000, 0
	s_add_i32 s36, s36, s38
	s_sub_i32 s37, s37, 0x6000
	s_cmp_lt_i32 s37, 0
	s_cselect_b32 s38, 0x12000, 0
	s_add_i32 s37, s37, s38
	v_subrev_u32_e32 v196, 0x6000, v177
	v_add_u32_e32 v198, 0xc000, v177
	v_min_u32_e32 v177, v196, v198
	s_add_i32 s1, s1, 1
	s_cmp_lt_u32 s1, 15
	s_waitcnt lgkmcnt(0)
	s_barrier
	s_cbranch_scc1 .Lg5_loop
	v_add_u32_e32 v190, s36, v186
	v_add_u32_e32 v191, s36, v187
	v_add_u32_e32 v250, s36, v188
	v_add_u32_e32 v251, s36, v189
	ds_read_b128 v[200:203], v190
	ds_read_b128 v[204:207], v190 offset:2048
	ds_read_b128 v[222:225], v250
	ds_read_b128 v[226:229], v250 offset:2048
	ds_read_b128 v[230:233], v250 offset:4096
	ds_read_b128 v[234:237], v250 offset:6144
	s_waitcnt lgkmcnt(3)
	v_mfma_f32_32x32x16_bf16 v[112:127], v[200:203], v[222:225], v[112:127]
	ds_read_b128 v[208:211], v191
	v_mfma_f32_32x32x16_bf16 v[48:63], v[204:207], v[222:225], v[48:63]
	ds_read_b128 v[212:215], v191 offset:2048
	s_waitcnt lgkmcnt(4)
	v_mfma_f32_32x32x16_bf16 v[96:111], v[200:203], v[226:229], v[96:111]
	ds_read_b128 v[238:241], v251
	v_mfma_f32_32x32x16_bf16 v[32:47], v[204:207], v[226:229], v[32:47]
	ds_read_b128 v[242:245], v251 offset:2048
	s_waitcnt lgkmcnt(5)
	v_mfma_f32_32x32x16_bf16 v[80:95], v[200:203], v[230:233], v[80:95]
	ds_read_b128 v[246:249], v251 offset:4096
	v_mfma_f32_32x32x16_bf16 v[16:31], v[204:207], v[230:233], v[16:31]
	ds_read_b128 v[192:195], v251 offset:6144
	s_waitcnt lgkmcnt(6)
	v_mfma_f32_32x32x16_bf16 v[64:79], v[200:203], v[234:237], v[64:79]
	v_mfma_f32_32x32x16_bf16 v[0:15], v[204:207], v[234:237], v[0:15]
	v_xad_u32 v190, v186, 64, s37
	v_xad_u32 v250, v188, 64, s37
	s_waitcnt lgkmcnt(3)
	v_mfma_f32_32x32x16_bf16 v[112:127], v[208:211], v[238:241], v[112:127]
	ds_read_b128 v[200:203], v190
	v_mfma_f32_32x32x16_bf16 v[48:63], v[212:215], v[238:241], v[48:63]
	ds_read_b128 v[204:207], v190 offset:2048
	s_waitcnt lgkmcnt(4)
	v_mfma_f32_32x32x16_bf16 v[96:111], v[208:211], v[242:245], v[96:111]
	ds_read_b128 v[222:225], v250
	v_mfma_f32_32x32x16_bf16 v[32:47], v[212:215], v[242:245], v[32:47]
	ds_read_b128 v[226:229], v250 offset:2048
	s_waitcnt lgkmcnt(5)
	v_mfma_f32_32x32x16_bf16 v[80:95], v[208:211], v[246:249], v[80:95]
	ds_read_b128 v[230:233], v250 offset:4096
	v_mfma_f32_32x32x16_bf16 v[16:31], v[212:215], v[246:249], v[16:31]
	ds_read_b128 v[234:237], v250 offset:6144
	s_waitcnt lgkmcnt(6)
	v_mfma_f32_32x32x16_bf16 v[64:79], v[208:211], v[192:195], v[64:79]
	v_mfma_f32_32x32x16_bf16 v[0:15], v[212:215], v[192:195], v[0:15]
	v_xad_u32 v191, v187, 64, s37
	v_xad_u32 v251, v189, 64, s37
	s_waitcnt lgkmcnt(3)
	v_mfma_f32_32x32x16_bf16 v[112:127], v[200:203], v[222:225], v[112:127]
	ds_read_b128 v[208:211], v191
	v_mfma_f32_32x32x16_bf16 v[48:63], v[204:207], v[222:225], v[48:63]
	ds_read_b128 v[212:215], v191 offset:2048
	s_waitcnt lgkmcnt(4)
	v_mfma_f32_32x32x16_bf16 v[96:111], v[200:203], v[226:229], v[96:111]
	ds_read_b128 v[238:241], v251
	v_mfma_f32_32x32x16_bf16 v[32:47], v[204:207], v[226:229], v[32:47]
	ds_read_b128 v[242:245], v251 offset:2048
	s_waitcnt lgkmcnt(5)
	v_mfma_f32_32x32x16_bf16 v[80:95], v[200:203], v[230:233], v[80:95]
	ds_read_b128 v[246:249], v251 offset:4096
	v_mfma_f32_32x32x16_bf16 v[16:31], v[204:207], v[230:233], v[16:31]
	ds_read_b128 v[192:195], v251 offset:6144
	s_waitcnt lgkmcnt(6)
	v_mfma_f32_32x32x16_bf16 v[64:79], v[200:203], v[234:237], v[64:79]
	v_mfma_f32_32x32x16_bf16 v[0:15], v[204:207], v[234:237], v[0:15]
	s_waitcnt lgkmcnt(3)
	v_mfma_f32_32x32x16_bf16 v[112:127], v[208:211], v[238:241], v[112:127]
	v_mfma_f32_32x32x16_bf16 v[48:63], v[212:215], v[238:241], v[48:63]
	s_waitcnt lgkmcnt(2)
	v_mfma_f32_32x32x16_bf16 v[96:111], v[208:211], v[242:245], v[96:111]
	v_mfma_f32_32x32x16_bf16 v[32:47], v[212:215], v[242:245], v[32:47]
	s_waitcnt lgkmcnt(1)
	v_mfma_f32_32x32x16_bf16 v[80:95], v[208:211], v[246:249], v[80:95]
	v_mfma_f32_32x32x16_bf16 v[16:31], v[212:215], v[246:249], v[16:31]
	s_waitcnt lgkmcnt(0)
	v_mfma_f32_32x32x16_bf16 v[64:79], v[208:211], v[192:195], v[64:79]
	v_mfma_f32_32x32x16_bf16 v[0:15], v[212:215], v[192:195], v[0:15]
	s_setprio 0
	s_nop 7
	s_nop 7
	s_branch .LBB0_482
	.p2align 6
	s_nop 0
	s_nop 0
	s_nop 0
	s_nop 0
	s_nop 0
	s_nop 0
	s_nop 0
	s_nop 0
	s_nop 0
	s_nop 0
	s_nop 0
	s_nop 0
	s_nop 0
	s_nop 0

.Lg6_noraise:
.Lg6_loop:
	v_add_u32_e32 v190, s40, v186
	v_add_u32_e32 v191, s40, v187
	v_add_u32_e32 v250, s40, v188
	v_add_u32_e32 v251, s40, v189
	ds_read_b128 v[200:203], v190
	ds_read_b128 v[204:207], v190 offset:2048
	ds_read_b128 v[222:225], v250
	ds_read_b128 v[226:229], v250 offset:2048
	ds_read_b128 v[230:233], v250 offset:4096
	ds_read_b128 v[234:237], v250 offset:6144
	s_waitcnt lgkmcnt(3)
	v_mfma_f32_32x32x16_bf16 v[112:127], v[200:203], v[222:225], v[112:127]
	global_load_dwordx4 v[128:131], v176, s[28:29]
	ds_read_b128 v[208:211], v191
	v_mfma_f32_32x32x16_bf16 v[48:63], v[204:207], v[222:225], v[48:63]
	global_load_dwordx4 v[132:135], v177, s[28:29]
	ds_read_b128 v[212:215], v191 offset:2048
	s_waitcnt lgkmcnt(4)
	v_mfma_f32_32x32x16_bf16 v[96:111], v[200:203], v[226:229], v[96:111]
	global_load_dwordx4 v[136:139], v178, s[28:29]
	ds_read_b128 v[238:241], v251
	v_mfma_f32_32x32x16_bf16 v[32:47], v[204:207], v[226:229], v[32:47]
	global_load_dwordx4 v[140:143], v179, s[28:29]
	ds_read_b128 v[242:245], v251 offset:2048
	s_waitcnt lgkmcnt(5)
	v_mfma_f32_32x32x16_bf16 v[80:95], v[200:203], v[230:233], v[80:95]
	global_load_dwordx4 v[144:147], v176, s[38:39]
	ds_read_b128 v[246:249], v251 offset:4096
	v_mfma_f32_32x32x16_bf16 v[16:31], v[204:207], v[230:233], v[16:31]
	global_load_dwordx4 v[148:151], v177, s[38:39]
	ds_read_b128 v[192:195], v251 offset:6144
	s_waitcnt lgkmcnt(6)
	v_mfma_f32_32x32x16_bf16 v[64:79], v[200:203], v[234:237], v[64:79]
	global_load_dwordx4 v[152:155], v178, s[38:39]
	v_mfma_f32_32x32x16_bf16 v[0:15], v[204:207], v[234:237], v[0:15]
	global_load_dwordx4 v[156:159], v179, s[38:39]
	v_xad_u32 v190, v186, 64, s41
	v_xad_u32 v250, v188, 64, s41
	s_waitcnt lgkmcnt(3)
	v_mfma_f32_32x32x16_bf16 v[112:127], v[208:211], v[238:241], v[112:127]
	global_load_dwordx4 v[160:163], v180, s[38:39]
	ds_read_b128 v[200:203], v190
	v_mfma_f32_32x32x16_bf16 v[48:63], v[212:215], v[238:241], v[48:63]
	global_load_dwordx4 v[164:167], v181, s[38:39]
	ds_read_b128 v[204:207], v190 offset:2048
	s_waitcnt lgkmcnt(4)
	v_mfma_f32_32x32x16_bf16 v[96:111], v[208:211], v[242:245], v[96:111]
	global_load_dwordx4 v[168:171], v182, s[38:39]
	ds_read_b128 v[222:225], v250
	v_mfma_f32_32x32x16_bf16 v[32:47], v[212:215], v[242:245], v[32:47]
	global_load_dwordx4 v[172:175], v184, s[38:39]
	ds_read_b128 v[226:229], v250 offset:2048
	s_waitcnt lgkmcnt(5)
	v_mfma_f32_32x32x16_bf16 v[80:95], v[208:211], v[246:249], v[80:95]
	ds_read_b128 v[230:233], v250 offset:4096
	v_mfma_f32_32x32x16_bf16 v[16:31], v[212:215], v[246:249], v[16:31]
	ds_read_b128 v[234:237], v250 offset:6144
	s_waitcnt lgkmcnt(6)
	v_mfma_f32_32x32x16_bf16 v[64:79], v[208:211], v[192:195], v[64:79]
	v_mfma_f32_32x32x16_bf16 v[0:15], v[212:215], v[192:195], v[0:15]
	s_barrier
	v_xad_u32 v191, v187, 64, s41
	v_xad_u32 v251, v189, 64, s41
	s_waitcnt lgkmcnt(3)
	v_mfma_f32_32x32x16_bf16 v[112:127], v[200:203], v[222:225], v[112:127]
	ds_read_b128 v[208:211], v191
	v_mfma_f32_32x32x16_bf16 v[48:63], v[204:207], v[222:225], v[48:63]
	ds_read_b128 v[212:215], v191 offset:2048
	s_waitcnt lgkmcnt(4)
	v_mfma_f32_32x32x16_bf16 v[96:111], v[200:203], v[226:229], v[96:111]
	ds_read_b128 v[238:241], v251
	s_waitcnt vmcnt(11)
	ds_write_b128 v185, v[128:131]
	v_mfma_f32_32x32x16_bf16 v[32:47], v[204:207], v[226:229], v[32:47]
	ds_read_b128 v[242:245], v251 offset:2048
	s_waitcnt vmcnt(10)
	ds_write_b128 v185, v[132:135] offset:2048
	s_waitcnt lgkmcnt(7)
	v_mfma_f32_32x32x16_bf16 v[80:95], v[200:203], v[230:233], v[80:95]
	ds_read_b128 v[246:249], v251 offset:4096
	s_waitcnt vmcnt(9)
	ds_write_b128 v185, v[136:139] offset:4096
	v_mfma_f32_32x32x16_bf16 v[16:31], v[204:207], v[230:233], v[16:31]
	ds_read_b128 v[192:195], v251 offset:6144
	s_waitcnt vmcnt(8)
	ds_write_b128 v185, v[140:143] offset:6144
	s_waitcnt lgkmcnt(10)
	v_mfma_f32_32x32x16_bf16 v[64:79], v[200:203], v[234:237], v[64:79]
	s_waitcnt vmcnt(7)
	ds_write_b128 v185, v[144:147] offset:8192
	v_mfma_f32_32x32x16_bf16 v[0:15], v[204:207], v[234:237], v[0:15]
	s_waitcnt vmcnt(6)
	ds_write_b128 v185, v[148:151] offset:10240
	s_waitcnt lgkmcnt(9)
	v_mfma_f32_32x32x16_bf16 v[112:127], v[208:211], v[238:241], v[112:127]
	s_waitcnt vmcnt(5)
	ds_write_b128 v185, v[152:155] offset:12288
	v_mfma_f32_32x32x16_bf16 v[48:63], v[212:215], v[238:241], v[48:63]
	s_waitcnt vmcnt(4)
	ds_write_b128 v185, v[156:159] offset:14336
	s_waitcnt lgkmcnt(9)
	v_mfma_f32_32x32x16_bf16 v[96:111], v[208:211], v[242:245], v[96:111]
	s_waitcnt vmcnt(3)
	ds_write_b128 v185, v[160:163] offset:16384
	v_mfma_f32_32x32x16_bf16 v[32:47], v[212:215], v[242:245], v[32:47]
	s_waitcnt vmcnt(2)
	ds_write_b128 v185, v[164:167] offset:18432
	s_waitcnt lgkmcnt(9)
	v_mfma_f32_32x32x16_bf16 v[80:95], v[208:211], v[246:249], v[80:95]
	s_waitcnt vmcnt(1)
	ds_write_b128 v185, v[168:171] offset:20480
	v_mfma_f32_32x32x16_bf16 v[16:31], v[212:215], v[246:249], v[16:31]
	s_waitcnt vmcnt(0)
	ds_write_b128 v185, v[172:175] offset:22528
	s_waitcnt lgkmcnt(9)
	v_mfma_f32_32x32x16_bf16 v[64:79], v[208:211], v[192:195], v[64:79]
	v_mfma_f32_32x32x16_bf16 v[0:15], v[212:215], v[192:195], v[0:15]
	s_add_u32 s28, s28, 0x80
	s_addc_u32 s29, s29, 0
	s_add_u32 s38, s38, 0x80
	s_addc_u32 s39, s39, 0
	s_sub_i32 s40, s40, 0x6000
	s_cmp_lt_i32 s40, 0
	s_cselect_b32 s42, 0x12000, 0
	s_add_i32 s40, s40, s42
	s_sub_i32 s41, s41, 0x6000
	s_cmp_lt_i32 s41, 0
	s_cselect_b32 s42, 0x12000, 0
	s_add_i32 s41, s41, s42
	v_subrev_u32_e32 v196, 0x6000, v185
	v_add_u32_e32 v198, 0xc000, v185
	v_min_u32_e32 v185, v196, v198
	s_add_i32 s7, s7, 1
	s_cmp_lt_u32 s7, 63
	s_waitcnt lgkmcnt(0)
	s_barrier
	s_cbranch_scc1 .Lg6_loop
	v_add_u32_e32 v190, s40, v186
	v_add_u32_e32 v191, s40, v187
	v_add_u32_e32 v250, s40, v188
	v_add_u32_e32 v251, s40, v189
	ds_read_b128 v[200:203], v190
	ds_read_b128 v[204:207], v190 offset:2048
	ds_read_b128 v[222:225], v250
	ds_read_b128 v[226:229], v250 offset:2048
	ds_read_b128 v[230:233], v250 offset:4096
	ds_read_b128 v[234:237], v250 offset:6144
	s_waitcnt lgkmcnt(3)
	v_mfma_f32_32x32x16_bf16 v[112:127], v[200:203], v[222:225], v[112:127]
	ds_read_b128 v[208:211], v191
	v_mfma_f32_32x32x16_bf16 v[48:63], v[204:207], v[222:225], v[48:63]
	ds_read_b128 v[212:215], v191 offset:2048
	s_waitcnt lgkmcnt(4)
	v_mfma_f32_32x32x16_bf16 v[96:111], v[200:203], v[226:229], v[96:111]
	ds_read_b128 v[238:241], v251
	v_mfma_f32_32x32x16_bf16 v[32:47], v[204:207], v[226:229], v[32:47]
	ds_read_b128 v[242:245], v251 offset:2048
	s_waitcnt lgkmcnt(5)
	v_mfma_f32_32x32x16_bf16 v[80:95], v[200:203], v[230:233], v[80:95]
	ds_read_b128 v[246:249], v251 offset:4096
	v_mfma_f32_32x32x16_bf16 v[16:31], v[204:207], v[230:233], v[16:31]
	ds_read_b128 v[192:195], v251 offset:6144
	s_waitcnt lgkmcnt(6)
	v_mfma_f32_32x32x16_bf16 v[64:79], v[200:203], v[234:237], v[64:79]
	v_mfma_f32_32x32x16_bf16 v[0:15], v[204:207], v[234:237], v[0:15]
	v_xad_u32 v190, v186, 64, s41
	v_xad_u32 v250, v188, 64, s41
	s_waitcnt lgkmcnt(3)
	v_mfma_f32_32x32x16_bf16 v[112:127], v[208:211], v[238:241], v[112:127]
	ds_read_b128 v[200:203], v190
	v_mfma_f32_32x32x16_bf16 v[48:63], v[212:215], v[238:241], v[48:63]
	ds_read_b128 v[204:207], v190 offset:2048
	s_waitcnt lgkmcnt(4)
	v_mfma_f32_32x32x16_bf16 v[96:111], v[208:211], v[242:245], v[96:111]
	ds_read_b128 v[222:225], v250
	v_mfma_f32_32x32x16_bf16 v[32:47], v[212:215], v[242:245], v[32:47]
	ds_read_b128 v[226:229], v250 offset:2048
	s_waitcnt lgkmcnt(5)
	v_mfma_f32_32x32x16_bf16 v[80:95], v[208:211], v[246:249], v[80:95]
	ds_read_b128 v[230:233], v250 offset:4096
	v_mfma_f32_32x32x16_bf16 v[16:31], v[212:215], v[246:249], v[16:31]
	ds_read_b128 v[234:237], v250 offset:6144
	s_waitcnt lgkmcnt(6)
	v_mfma_f32_32x32x16_bf16 v[64:79], v[208:211], v[192:195], v[64:79]
	v_mfma_f32_32x32x16_bf16 v[0:15], v[212:215], v[192:195], v[0:15]
	v_xad_u32 v191, v187, 64, s41
	v_xad_u32 v251, v189, 64, s41
	s_waitcnt lgkmcnt(3)
	v_mfma_f32_32x32x16_bf16 v[112:127], v[200:203], v[222:225], v[112:127]
	ds_read_b128 v[208:211], v191
	v_mfma_f32_32x32x16_bf16 v[48:63], v[204:207], v[222:225], v[48:63]
	ds_read_b128 v[212:215], v191 offset:2048
	s_waitcnt lgkmcnt(4)
	v_mfma_f32_32x32x16_bf16 v[96:111], v[200:203], v[226:229], v[96:111]
	ds_read_b128 v[238:241], v251
	v_mfma_f32_32x32x16_bf16 v[32:47], v[204:207], v[226:229], v[32:47]
	ds_read_b128 v[242:245], v251 offset:2048
	s_waitcnt lgkmcnt(5)
	v_mfma_f32_32x32x16_bf16 v[80:95], v[200:203], v[230:233], v[80:95]
	ds_read_b128 v[246:249], v251 offset:4096
	v_mfma_f32_32x32x16_bf16 v[16:31], v[204:207], v[230:233], v[16:31]
	ds_read_b128 v[192:195], v251 offset:6144
	s_waitcnt lgkmcnt(6)
	v_mfma_f32_32x32x16_bf16 v[64:79], v[200:203], v[234:237], v[64:79]
	v_mfma_f32_32x32x16_bf16 v[0:15], v[204:207], v[234:237], v[0:15]
	s_waitcnt lgkmcnt(3)
	v_mfma_f32_32x32x16_bf16 v[112:127], v[208:211], v[238:241], v[112:127]
	v_mfma_f32_32x32x16_bf16 v[48:63], v[212:215], v[238:241], v[48:63]
	s_waitcnt lgkmcnt(2)
	v_mfma_f32_32x32x16_bf16 v[96:111], v[208:211], v[242:245], v[96:111]
	v_mfma_f32_32x32x16_bf16 v[32:47], v[212:215], v[242:245], v[32:47]
	s_waitcnt lgkmcnt(1)
	v_mfma_f32_32x32x16_bf16 v[80:95], v[208:211], v[246:249], v[80:95]
	v_mfma_f32_32x32x16_bf16 v[16:31], v[212:215], v[246:249], v[16:31]
	s_waitcnt lgkmcnt(0)
	v_mfma_f32_32x32x16_bf16 v[64:79], v[208:211], v[192:195], v[64:79]
	v_mfma_f32_32x32x16_bf16 v[0:15], v[212:215], v[192:195], v[0:15]
	s_setprio 0
	s_nop 7
	s_nop 7
	.p2align 6
	s_nop 0

.Lg7_noraise:
.Lg7_loop:
	v_add_u32_e32 v209, s98, v205
	v_add_u32_e32 v210, s98, v206
	v_add_u32_e32 v211, s98, v207
	v_add_u32_e32 v212, s98, v208
	ds_read_b128 v[160:163], v209
	ds_read_b128 v[164:167], v209 offset:2048
	ds_read_b128 v[168:171], v211
	ds_read_b128 v[172:175], v211 offset:2048
	s_waitcnt lgkmcnt(1)
	v_mfma_f32_32x32x16_bf16 v[112:127], v[160:163], v[168:171], v[112:127]
	global_load_dwordx4 v[128:131], v200, s[6:7]
	ds_read_b128 v[176:179], v210
	v_mfma_f32_32x32x16_bf16 v[48:63], v[164:167], v[168:171], v[48:63]
	global_load_dwordx4 v[132:135], v201, s[6:7]
	ds_read_b128 v[180:183], v210 offset:2048
	s_waitcnt lgkmcnt(2)
	v_mfma_f32_32x32x16_bf16 v[96:111], v[160:163], v[172:175], v[96:111]
	global_load_dwordx4 v[136:139], v202, s[6:7]
	ds_read_b128 v[184:187], v212
	v_mfma_f32_32x32x16_bf16 v[32:47], v[164:167], v[172:175], v[32:47]
	global_load_dwordx4 v[140:143], v203, s[6:7]
	ds_read_b128 v[188:191], v212 offset:2048
	v_xad_u32 v209, v205, 64, s99
	v_xad_u32 v211, v207, 64, s99
	s_waitcnt lgkmcnt(1)
	v_mfma_f32_32x32x16_bf16 v[112:127], v[176:179], v[184:187], v[112:127]
	global_load_dwordx4 v[144:147], v200, s[8:9]
	ds_read_b128 v[160:163], v209
	v_mfma_f32_32x32x16_bf16 v[48:63], v[180:183], v[184:187], v[48:63]
	global_load_dwordx4 v[148:151], v201, s[8:9]
	ds_read_b128 v[164:167], v209 offset:2048
	s_waitcnt lgkmcnt(2)
	v_mfma_f32_32x32x16_bf16 v[96:111], v[176:179], v[188:191], v[96:111]
	global_load_dwordx4 v[152:155], v202, s[8:9]
	ds_read_b128 v[168:171], v211
	v_mfma_f32_32x32x16_bf16 v[32:47], v[180:183], v[188:191], v[32:47]
	global_load_dwordx4 v[156:159], v203, s[8:9]
	ds_read_b128 v[172:175], v211 offset:2048
	s_barrier
	v_xad_u32 v210, v206, 64, s99
	v_xad_u32 v212, v208, 64, s99
	s_waitcnt lgkmcnt(1)
	v_mfma_f32_32x32x16_bf16 v[112:127], v[160:163], v[168:171], v[112:127]
	ds_read_b128 v[176:179], v210
	v_mfma_f32_32x32x16_bf16 v[48:63], v[164:167], v[168:171], v[48:63]
	ds_read_b128 v[180:183], v210 offset:2048
	s_waitcnt lgkmcnt(2)
	v_mfma_f32_32x32x16_bf16 v[96:111], v[160:163], v[172:175], v[96:111]
	ds_read_b128 v[184:187], v212
	s_waitcnt vmcnt(7)
	ds_write_b128 v204, v[128:131]
	v_mfma_f32_32x32x16_bf16 v[32:47], v[164:167], v[172:175], v[32:47]
	ds_read_b128 v[188:191], v212 offset:2048
	s_waitcnt vmcnt(6)
	ds_write_b128 v204, v[132:135] offset:2048
	s_waitcnt lgkmcnt(3)
	v_mfma_f32_32x32x16_bf16 v[112:127], v[176:179], v[184:187], v[112:127]
	s_waitcnt vmcnt(5)
	ds_write_b128 v204, v[136:139] offset:4096
	v_mfma_f32_32x32x16_bf16 v[48:63], v[180:183], v[184:187], v[48:63]
	s_waitcnt vmcnt(4)
	ds_write_b128 v204, v[140:143] offset:6144
	s_waitcnt lgkmcnt(3)
	v_mfma_f32_32x32x16_bf16 v[96:111], v[176:179], v[188:191], v[96:111]
	s_waitcnt vmcnt(3)
	ds_write_b128 v204, v[144:147] offset:8192
	v_mfma_f32_32x32x16_bf16 v[32:47], v[180:183], v[188:191], v[32:47]
	s_waitcnt vmcnt(2)
	ds_write_b128 v204, v[148:151] offset:10240
	s_waitcnt vmcnt(1)
	ds_write_b128 v204, v[152:155] offset:12288
	s_waitcnt vmcnt(0)
	ds_write_b128 v204, v[156:159] offset:14336
	s_add_u32 s6, s6, 0x80
	s_addc_u32 s7, s7, 0
	s_add_u32 s8, s8, 0x80
	s_addc_u32 s9, s9, 0
	s_sub_i32 s98, s98, 0x4000
	s_cmp_lt_i32 s98, 0
	s_cselect_b32 s101, 0xc000, 0
	s_add_i32 s98, s98, s101
	s_sub_i32 s99, s99, 0x4000
	s_cmp_lt_i32 s99, 0
	s_cselect_b32 s101, 0xc000, 0
	s_add_i32 s99, s99, s101
	v_subrev_u32_e32 v213, 0x4000, v204
	v_add_u32_e32 v214, 0x8000, v204
	v_min_u32_e32 v204, v213, v214
	s_add_i32 s100, s100, 1
	s_cmp_lt_u32 s100, 15
	s_waitcnt lgkmcnt(0)
	s_barrier
	s_cbranch_scc1 .Lg7_loop
	v_add_u32_e32 v209, s98, v205
	v_add_u32_e32 v210, s98, v206
	v_add_u32_e32 v211, s98, v207
	v_add_u32_e32 v212, s98, v208
	ds_read_b128 v[160:163], v209
	ds_read_b128 v[164:167], v209 offset:2048
	ds_read_b128 v[168:171], v211
	ds_read_b128 v[172:175], v211 offset:2048
	s_waitcnt lgkmcnt(1)
	v_mfma_f32_32x32x16_bf16 v[112:127], v[160:163], v[168:171], v[112:127]
	ds_read_b128 v[176:179], v210
	v_mfma_f32_32x32x16_bf16 v[48:63], v[164:167], v[168:171], v[48:63]
	ds_read_b128 v[180:183], v210 offset:2048
	s_waitcnt lgkmcnt(2)
	v_mfma_f32_32x32x16_bf16 v[96:111], v[160:163], v[172:175], v[96:111]
	ds_read_b128 v[184:187], v212
	v_mfma_f32_32x32x16_bf16 v[32:47], v[164:167], v[172:175], v[32:47]
	ds_read_b128 v[188:191], v212 offset:2048
	v_xad_u32 v209, v205, 64, s99
	v_xad_u32 v211, v207, 64, s99
	s_waitcnt lgkmcnt(1)
	v_mfma_f32_32x32x16_bf16 v[112:127], v[176:179], v[184:187], v[112:127]
	ds_read_b128 v[160:163], v209
	v_mfma_f32_32x32x16_bf16 v[48:63], v[180:183], v[184:187], v[48:63]
	ds_read_b128 v[164:167], v209 offset:2048
	s_waitcnt lgkmcnt(2)
	v_mfma_f32_32x32x16_bf16 v[96:111], v[176:179], v[188:191], v[96:111]
	ds_read_b128 v[168:171], v211
	v_mfma_f32_32x32x16_bf16 v[32:47], v[180:183], v[188:191], v[32:47]
	ds_read_b128 v[172:175], v211 offset:2048
	v_xad_u32 v210, v206, 64, s99
	v_xad_u32 v212, v208, 64, s99
	s_waitcnt lgkmcnt(1)
	v_mfma_f32_32x32x16_bf16 v[112:127], v[160:163], v[168:171], v[112:127]
	ds_read_b128 v[176:179], v210
	v_mfma_f32_32x32x16_bf16 v[48:63], v[164:167], v[168:171], v[48:63]
	ds_read_b128 v[180:183], v210 offset:2048
	s_waitcnt lgkmcnt(2)
	v_mfma_f32_32x32x16_bf16 v[96:111], v[160:163], v[172:175], v[96:111]
	ds_read_b128 v[184:187], v212
	v_mfma_f32_32x32x16_bf16 v[32:47], v[164:167], v[172:175], v[32:47]
	ds_read_b128 v[188:191], v212 offset:2048
	s_waitcnt lgkmcnt(1)
	v_mfma_f32_32x32x16_bf16 v[112:127], v[176:179], v[184:187], v[112:127]
	v_mfma_f32_32x32x16_bf16 v[48:63], v[180:183], v[184:187], v[48:63]
	s_waitcnt lgkmcnt(0)
	v_mfma_f32_32x32x16_bf16 v[96:111], v[176:179], v[188:191], v[96:111]
	v_mfma_f32_32x32x16_bf16 v[32:47], v[180:183], v[188:191], v[32:47]
	s_setprio 0
	s_nop 7
	s_nop 7
	s_lshl_b32 s1, s38, 1
	s_and_b32 s1, s1, 0xffffff00
	v_lshrrev_b32_e32 v128, 1, v192
	s_add_i32 s1, s1, 0
	v_and_b32_e32 v128, 16, v128
	v_add_u32_e32 v128, s1, v128
	v_add_u32_e32 v163, 0x12000, v128
	s_barrier
	ds_read_b128 v[140:143], v163
	ds_read_b128 v[136:139], v163 offset:32
	ds_read_b128 v[132:135], v163 offset:64
	ds_read_b128 v[128:131], v163 offset:96
	v_mov_b32_e32 v208, v197
	s_waitcnt lgkmcnt(3)
	v_mul_f32_e32 v112, v112, v140
	v_mul_f32_e32 v112, 0xbfb8aa3b, v112
	v_exp_f32_e32 v112, v112
	s_nop 0
	v_add_f32_e32 v112, 1.0, v112
	v_rcp_f32_e32 v112, v112
	s_nop 0
	v_mul_f32_e32 v159, v80, v112
	v_mul_f32_e32 v80, v113, v141
	v_mul_f32_e32 v80, 0xbfb8aa3b, v80
	v_exp_f32_e32 v80, v80
	s_nop 0
	v_add_f32_e32 v80, 1.0, v80
	v_rcp_f32_e32 v80, v80
	s_nop 0
	v_mul_f32_e32 v161, v81, v80
	v_mul_f32_e32 v80, v114, v142
	v_mul_f32_e32 v80, 0xbfb8aa3b, v80
	v_exp_f32_e32 v80, v80
	s_nop 0
	v_add_f32_e32 v80, 1.0, v80
	v_rcp_f32_e32 v80, v80
	s_nop 0
	v_mul_f32_e32 v162, v82, v80
	v_mul_f32_e32 v80, v115, v143
	v_mul_f32_e32 v80, 0xbfb8aa3b, v80
	v_exp_f32_e32 v80, v80
	s_nop 0
	v_add_f32_e32 v80, 1.0, v80
	v_rcp_f32_e32 v80, v80
	s_nop 0
	v_mul_f32_e32 v160, v83, v80
	s_waitcnt lgkmcnt(2)
	v_mul_f32_e32 v80, v116, v136
	v_mul_f32_e32 v80, 0xbfb8aa3b, v80
	v_exp_f32_e32 v80, v80
	s_nop 0
	v_add_f32_e32 v80, 1.0, v80
	v_rcp_f32_e32 v80, v80
	s_nop 0
	v_mul_f32_e32 v158, v84, v80
	v_mul_f32_e32 v80, v117, v137
	v_mul_f32_e32 v80, 0xbfb8aa3b, v80
	v_exp_f32_e32 v80, v80
	s_nop 0
	v_add_f32_e32 v80, 1.0, v80
	v_rcp_f32_e32 v80, v80
	s_nop 0
	v_mul_f32_e32 v157, v85, v80
	v_mul_f32_e32 v80, v118, v138
	v_mul_f32_e32 v80, 0xbfb8aa3b, v80
	v_exp_f32_e32 v80, v80
	s_nop 0
	v_add_f32_e32 v80, 1.0, v80
	v_rcp_f32_e32 v80, v80
	s_nop 0
	v_mul_f32_e32 v156, v86, v80
	v_mul_f32_e32 v80, v119, v139
	v_mul_f32_e32 v80, 0xbfb8aa3b, v80
	v_exp_f32_e32 v80, v80
	s_nop 0
	v_add_f32_e32 v80, 1.0, v80
	v_rcp_f32_e32 v80, v80
	s_nop 0
	v_mul_f32_e32 v155, v87, v80
	s_waitcnt lgkmcnt(1)
	v_mul_f32_e32 v80, v120, v132
	v_mul_f32_e32 v80, 0xbfb8aa3b, v80
	v_exp_f32_e32 v80, v80
	s_nop 0
	v_add_f32_e32 v80, 1.0, v80
	v_rcp_f32_e32 v80, v80
	s_nop 0
	v_mul_f32_e32 v154, v88, v80
	v_mul_f32_e32 v80, v121, v133
	v_mul_f32_e32 v80, 0xbfb8aa3b, v80
	v_exp_f32_e32 v80, v80
	s_nop 0
	v_add_f32_e32 v80, 1.0, v80
	v_rcp_f32_e32 v80, v80
	s_nop 0
	v_mul_f32_e32 v153, v89, v80
	v_mul_f32_e32 v80, v122, v134
	v_mul_f32_e32 v80, 0xbfb8aa3b, v80
	v_exp_f32_e32 v80, v80
	s_nop 0
	v_add_f32_e32 v80, 1.0, v80
	v_rcp_f32_e32 v80, v80
	s_nop 0
	v_mul_f32_e32 v152, v90, v80
	v_mul_f32_e32 v80, v123, v135
	v_mul_f32_e32 v80, 0xbfb8aa3b, v80
	v_exp_f32_e32 v80, v80
	s_nop 0
	v_add_f32_e32 v80, 1.0, v80
	v_rcp_f32_e32 v80, v80
	s_nop 0
	v_mul_f32_e32 v151, v91, v80
	s_waitcnt lgkmcnt(0)
	v_mul_f32_e32 v80, v124, v128
	v_mul_f32_e32 v80, 0xbfb8aa3b, v80
	v_exp_f32_e32 v80, v80
	s_nop 0
	v_add_f32_e32 v80, 1.0, v80
	v_rcp_f32_e32 v80, v80
	s_nop 0
	v_mul_f32_e32 v150, v92, v80
	v_mul_f32_e32 v80, v125, v129
	v_mul_f32_e32 v80, 0xbfb8aa3b, v80
	v_exp_f32_e32 v80, v80
	s_nop 0
	v_add_f32_e32 v80, 1.0, v80
	v_rcp_f32_e32 v80, v80
	s_nop 0
	v_mul_f32_e32 v149, v93, v80
	v_mul_f32_e32 v80, v126, v130
	v_mul_f32_e32 v80, 0xbfb8aa3b, v80
	v_exp_f32_e32 v80, v80
	s_nop 0
	v_add_f32_e32 v80, 1.0, v80
	v_rcp_f32_e32 v80, v80
	s_nop 0
	v_mul_f32_e32 v148, v94, v80
	v_mul_f32_e32 v80, v127, v131
	v_mul_f32_e32 v80, 0xbfb8aa3b, v80
	v_exp_f32_e32 v80, v80
	s_nop 0
	v_add_f32_e32 v80, 1.0, v80
	v_rcp_f32_e32 v80, v80
	s_nop 0
	v_mul_f32_e32 v147, v95, v80
	v_mul_f32_e32 v80, v96, v140
	v_mul_f32_e32 v80, 0xbfb8aa3b, v80
	v_exp_f32_e32 v80, v80
	s_nop 0
	v_add_f32_e32 v80, 1.0, v80
	v_rcp_f32_e32 v80, v80
	s_nop 0
	v_mul_f32_e32 v144, v64, v80
	v_mul_f32_e32 v64, v97, v141
	v_mul_f32_e32 v64, 0xbfb8aa3b, v64
	v_exp_f32_e32 v64, v64
	s_nop 0
	v_add_f32_e32 v64, 1.0, v64
	v_rcp_f32_e32 v64, v64
	s_nop 0
	v_mul_f32_e32 v146, v65, v64
	v_mul_f32_e32 v64, v98, v142
	v_mul_f32_e32 v64, 0xbfb8aa3b, v64
	v_exp_f32_e32 v64, v64
	v_mul_f32_e32 v169, v146, v146
	v_fmac_f32_e32 v169, v161, v161
	v_add_f32_e32 v64, 1.0, v64
	v_rcp_f32_e32 v64, v64
	s_nop 0
	v_mul_f32_e32 v145, v66, v64
	v_mul_f32_e32 v64, v99, v143
	v_mul_f32_e32 v64, 0xbfb8aa3b, v64
	v_exp_f32_e32 v64, v64
	s_nop 0
	v_add_f32_e32 v64, 1.0, v64
	v_rcp_f32_e32 v64, v64
	s_nop 0
	v_mul_f32_e32 v143, v67, v64
	v_mul_f32_e32 v64, v100, v136
	v_mul_f32_e32 v64, 0xbfb8aa3b, v64
	v_exp_f32_e32 v64, v64
	s_nop 0
	v_add_f32_e32 v64, 1.0, v64
	v_rcp_f32_e32 v64, v64
	s_nop 0
	v_mul_f32_e32 v142, v68, v64
	v_mul_f32_e32 v64, v101, v137
	v_mul_f32_e32 v64, 0xbfb8aa3b, v64
	v_exp_f32_e32 v64, v64
	v_mul_f32_e32 v177, v142, v142
	v_fmac_f32_e32 v177, v158, v158
	v_add_f32_e32 v64, 1.0, v64
	v_rcp_f32_e32 v64, v64
	s_nop 0
	v_mul_f32_e32 v141, v69, v64
	v_mul_f32_e32 v64, v102, v138
	v_mul_f32_e32 v64, 0xbfb8aa3b, v64
	v_exp_f32_e32 v64, v64
	v_mul_f32_e32 v179, v141, v141
	v_fmac_f32_e32 v179, v157, v157
	v_add_f32_e32 v64, 1.0, v64
	v_rcp_f32_e32 v64, v64
	s_nop 0
	v_mul_f32_e32 v140, v70, v64
	v_mul_f32_e32 v64, v103, v139
	v_mul_f32_e32 v64, 0xbfb8aa3b, v64
	v_exp_f32_e32 v64, v64
	v_mul_f32_e32 v180, v140, v140
	v_fmac_f32_e32 v180, v156, v156
	v_add_f32_e32 v64, 1.0, v64
	v_rcp_f32_e32 v64, v64
	s_nop 0
	v_mul_f32_e32 v138, v71, v64
	v_mul_f32_e32 v64, v104, v132
	v_mul_f32_e32 v64, 0xbfb8aa3b, v64
	v_exp_f32_e32 v64, v64
	v_mul_f32_e32 v182, v138, v138
	v_fmac_f32_e32 v182, v155, v155
	v_add_f32_e32 v64, 1.0, v64
	v_rcp_f32_e32 v64, v64
	s_nop 0
	v_mul_f32_e32 v137, v72, v64
	v_mul_f32_e32 v64, v105, v133
	v_mul_f32_e32 v64, 0xbfb8aa3b, v64
	v_exp_f32_e32 v64, v64
	v_mul_f32_e32 v184, v137, v137
	v_fmac_f32_e32 v184, v154, v154
	v_add_f32_e32 v64, 1.0, v64
	v_rcp_f32_e32 v64, v64
	s_nop 0
	v_mul_f32_e32 v136, v73, v64
	v_mul_f32_e32 v64, v106, v134
	v_mul_f32_e32 v64, 0xbfb8aa3b, v64
	v_exp_f32_e32 v64, v64
	s_nop 0
	v_add_f32_e32 v64, 1.0, v64
	v_rcp_f32_e32 v64, v64
	s_nop 0
	v_mul_f32_e32 v134, v74, v64
	v_mul_f32_e32 v64, v107, v135
	v_mul_f32_e32 v64, 0xbfb8aa3b, v64
	v_exp_f32_e32 v64, v64
	s_nop 0
	v_add_f32_e32 v64, 1.0, v64
	v_rcp_f32_e32 v64, v64
	s_nop 0
	v_mul_f32_e32 v133, v75, v64
	v_mul_f32_e32 v64, v108, v128
	v_mul_f32_e32 v64, 0xbfb8aa3b, v64
	v_exp_f32_e32 v64, v64
	v_mul_f32_e32 v189, v133, v133
	v_fmac_f32_e32 v189, v151, v151
	v_add_f32_e32 v64, 1.0, v64
	v_rcp_f32_e32 v64, v64
	s_nop 0
	v_mul_f32_e32 v132, v76, v64
	v_mul_f32_e32 v64, v109, v129
	v_mul_f32_e32 v64, 0xbfb8aa3b, v64
	v_exp_f32_e32 v64, v64
	v_mul_f32_e32 v196, v132, v132
	v_fmac_f32_e32 v196, v150, v150
	v_add_f32_e32 v64, 1.0, v64
	v_rcp_f32_e32 v64, v64
	s_nop 0
	v_mul_f32_e32 v128, v77, v64
	v_mul_f32_e32 v64, v110, v130
	v_mul_f32_e32 v64, 0xbfb8aa3b, v64
	v_exp_f32_e32 v64, v64
	s_nop 0
	v_add_f32_e32 v64, 1.0, v64
	v_rcp_f32_e32 v64, v64
	s_nop 0
	v_mul_f32_e32 v125, v78, v64
	v_mul_f32_e32 v64, v111, v131
	v_mul_f32_e32 v64, 0xbfb8aa3b, v64
	v_exp_f32_e32 v64, v64
	v_mul_f32_e32 v209, v125, v125
	v_fmac_f32_e32 v209, v148, v148
	v_add_f32_e32 v64, 1.0, v64
	v_rcp_f32_e32 v64, v64
	s_nop 0
	v_mul_f32_e32 v127, v79, v64
	ds_read_b128 v[76:79], v163 offset:128
	ds_read_b128 v[72:75], v163 offset:160
	ds_read_b128 v[68:71], v163 offset:192
	ds_read_b128 v[64:67], v163 offset:224
	s_nop 0
	v_readfirstlane_b32 s1, v208
	s_ashr_i32 s7, s1, 7
	s_bfe_u32 s8, s1, 0x10006
	s_lshl_b32 s1, s68, 1
	v_bfe_u32 v205, v208, 5, 1
	s_and_b32 s6, s1, 14
	s_lshl_b32 s1, s7, 6
	s_add_i32 s9, s1, s0
	v_lshlrev_b32_e32 v84, 2, v205
	v_or_b32_e32 v86, s9, v84
	s_lshl_b32 s9, s93, 1
	s_add_u32 s9, s66, s9
	s_addc_u32 s37, s67, 0
	s_lshl_b32 s36, s8, 7
	v_and_b32_e32 v206, 31, v208
	s_add_u32 s36, s9, s36
	s_addc_u32 s37, s37, 0
	v_lshlrev_b32_e32 v198, 1, v206
	v_ashrrev_i32_e32 v87, 31, v86
	v_lshl_add_u64 v[90:91], s[36:37], 0, v[198:199]
	v_lshlrev_b64 v[88:89], 11, v[86:87]
	v_lshl_add_u64 v[80:81], v[90:91], 0, v[88:89]
	v_add_co_u32_e32 v82, vcc, s96, v80
	global_load_ushort v207, v[80:81], off
	global_load_ushort v204, v[80:81], off offset:2048
	v_addc_co_u32_e32 v83, vcc, 0, v81, vcc
	v_add_co_u32_e32 v92, vcc, s94, v80
	global_load_ushort v203, v[82:83], off
	global_load_ushort v202, v[82:83], off offset:2048
	v_addc_co_u32_e32 v93, vcc, 0, v81, vcc
	v_add_co_u32_e32 v94, vcc, s57, v80
	v_and_b32_e32 v85, 16, v208
	s_nop 0
	v_addc_co_u32_e32 v95, vcc, 0, v81, vcc
	v_add_co_u32_e32 v96, vcc, s35, v80
	global_load_ushort v201, v[94:95], off offset:-4096
	global_load_ushort v200, v[92:93], off offset:2048
	global_load_ushort v195, v[94:95], off
	global_load_ushort v194, v[94:95], off offset:2048
	v_addc_co_u32_e32 v97, vcc, 0, v81, vcc
	v_add_co_u32_e32 v98, vcc, s58, v80
	v_cmp_eq_u32_e64 s[42:43], 0, v85
	s_nop 0
	v_addc_co_u32_e32 v99, vcc, 0, v81, vcc
	v_add_co_u32_e32 v100, vcc, s95, v80
	global_load_ushort v193, v[98:99], off offset:-4096
	global_load_ushort v192, v[96:97], off offset:2048
	global_load_ushort v191, v[98:99], off
	global_load_ushort v190, v[98:99], off offset:2048
	v_addc_co_u32_e32 v101, vcc, 0, v81, vcc
	v_add_co_u32_e32 v102, vcc, s59, v80
	v_and_b32_e32 v85, 8, v208
	s_nop 0
	v_addc_co_u32_e32 v103, vcc, 0, v81, vcc
	global_load_ushort v188, v[102:103], off offset:-4096
	global_load_ushort v185, v[100:101], off offset:2048
	global_load_ushort v183, v[102:103], off
	global_load_ushort v181, v[102:103], off offset:2048
	global_load_ushort v178, v[80:81], off offset:64
	global_load_ushort v176, v[80:81], off offset:2112
	global_load_ushort v174, v[82:83], off offset:64
	global_load_ushort v175, v[82:83], off offset:2112
	global_load_ushort v171, v[92:93], off offset:64
	global_load_ushort v170, v[92:93], off offset:2112
	global_load_ushort v168, v[94:95], off offset:64
	global_load_ushort v167, v[94:95], off offset:2112
	global_load_ushort v166, v[96:97], off offset:64
	global_load_ushort v165, v[96:97], off offset:2112
	global_load_ushort v164, v[98:99], off offset:64
	global_load_ushort v163, v[98:99], off offset:2112
	global_load_ushort v139, v[100:101], off offset:64
	global_load_ushort v135, v[100:101], off offset:2112
	global_load_ushort v131, v[102:103], off offset:64
	global_load_ushort v130, v[102:103], off offset:2112
	v_or_b32_e32 v80, 32, v86
	v_ashrrev_i32_e32 v81, 31, v80
	v_lshlrev_b64 v[82:83], 11, v[80:81]
	v_lshl_add_u64 v[90:91], v[90:91], 0, v[82:83]
	v_add_co_u32_e32 v92, vcc, s96, v90
	global_load_ushort v129, v[90:91], off
	global_load_ushort v126, v[90:91], off offset:2048
	v_addc_co_u32_e32 v93, vcc, 0, v91, vcc
	v_add_co_u32_e32 v94, vcc, s94, v90
	global_load_ushort v124, v[92:93], off
	global_load_ushort v123, v[92:93], off offset:2048
	v_addc_co_u32_e32 v95, vcc, 0, v91, vcc
	v_add_co_u32_e32 v96, vcc, s57, v90
	v_cmp_eq_u32_e64 s[38:39], 0, v85
	s_nop 0
	v_addc_co_u32_e32 v97, vcc, 0, v91, vcc
	v_add_co_u32_e32 v98, vcc, s35, v90
	global_load_ushort v122, v[96:97], off offset:-4096
	global_load_ushort v121, v[94:95], off offset:2048
	global_load_ushort v120, v[96:97], off
	global_load_ushort v119, v[96:97], off offset:2048
	v_addc_co_u32_e32 v99, vcc, 0, v91, vcc
	v_add_co_u32_e32 v172, vcc, s58, v90
	v_xor_b32_e32 v85, 8, v219
	s_nop 0
	v_addc_co_u32_e32 v173, vcc, 0, v91, vcc
	v_add_co_u32_e32 v186, vcc, s95, v90
	global_load_ushort v118, v[172:173], off offset:-4096
	global_load_ushort v117, v[98:99], off offset:2048
	global_load_ushort v116, v[172:173], off
	global_load_ushort v115, v[172:173], off offset:2048
	v_addc_co_u32_e32 v187, vcc, 0, v91, vcc
	v_add_co_u32_e32 v210, vcc, s59, v90
	v_mul_f32_e32 v198, v128, v128
	s_nop 0
	v_addc_co_u32_e32 v211, vcc, 0, v91, vcc
	global_load_ushort v114, v[210:211], off offset:-4096
	global_load_ushort v113, v[186:187], off offset:2048
	global_load_ushort v112, v[210:211], off
	global_load_ushort v111, v[210:211], off offset:2048
	global_load_ushort v110, v[90:91], off offset:64
	global_load_ushort v108, v[90:91], off offset:2112
	global_load_ushort v109, v[92:93], off offset:64
	global_load_ushort v107, v[92:93], off offset:2112
	global_load_ushort v106, v[94:95], off offset:64
	global_load_ushort v105, v[94:95], off offset:2112
	global_load_ushort v104, v[96:97], off offset:64
	global_load_ushort v103, v[96:97], off offset:2112
	global_load_ushort v102, v[98:99], off offset:64
	global_load_ushort v101, v[98:99], off offset:2112
	global_load_ushort v100, v[172:173], off offset:64
	s_nop 0
	global_load_ushort v99, v[172:173], off offset:2112
	global_load_ushort v98, v[186:187], off offset:64
	global_load_ushort v97, v[186:187], off offset:2112
	global_load_ushort v95, v[210:211], off offset:64
	global_load_ushort v96, v[210:211], off offset:2112
	v_and_b32_e32 v92, 64, v219
	v_xor_b32_e32 v91, 16, v219
	v_add_u32_e32 v92, 64, v92
	v_cmp_lt_i32_e32 vcc, v91, v92
	v_and_b32_e32 v90, 4, v208
	v_cmp_eq_u32_e64 s[36:37], 0, v90
	v_cndmask_b32_e32 v91, v219, v91, vcc
	v_cmp_lt_i32_e32 vcc, v85, v92
	v_lshlrev_b32_e32 v94, 2, v91
	v_mul_f32_e32 v186, v136, v136
	v_cndmask_b32_e32 v85, v219, v85, vcc
	v_lshlrev_b32_e32 v93, 2, v85
	v_xor_b32_e32 v85, 4, v219
	v_cmp_lt_i32_e32 vcc, v85, v92
	v_fmac_f32_e32 v186, v153, v153
	v_mul_f32_e32 v172, v145, v145
	v_cndmask_b32_e32 v85, v219, v85, vcc
	v_lshlrev_b32_e32 v90, 2, v85
	v_and_b32_e32 v85, 2, v208
	v_cmp_eq_u32_e64 s[40:41], 0, v85
	v_xor_b32_e32 v85, 2, v219
	v_cmp_lt_i32_e32 vcc, v85, v92
	v_mul_f32_e32 v187, v134, v134
	v_fmac_f32_e32 v172, v162, v162
	v_cndmask_b32_e32 v85, v219, v85, vcc
	v_lshlrev_b32_e32 v91, 2, v85
	v_xor_b32_e32 v85, 1, v219
	v_cmp_lt_i32_e32 vcc, v85, v92
	v_fmac_f32_e32 v187, v152, v152
	v_mul_f32_e32 v173, v143, v143
	v_cndmask_b32_e32 v85, v219, v85, vcc
	v_lshlrev_b32_e32 v92, 2, v85
	v_and_b32_e32 v85, 1, v208
	v_cmp_eq_u32_e64 s[44:45], 0, v85
	v_bfe_u32 v85, v208, 1, 2
	v_and_or_b32 v85, v208, 24, v85
	v_or3_b32 v84, v85, s0, v84
	v_mul_f32_e32 v85, v144, v144
	v_fmac_f32_e32 v85, v159, v159
	v_cndmask_b32_e64 v211, v184, v85, s[42:43]
	v_cndmask_b32_e64 v85, v85, v184, s[42:43]
	v_cndmask_b32_e64 v184, v186, v169, s[42:43]
	v_cndmask_b32_e64 v169, v169, v186, s[42:43]
	ds_bpermute_b32 v169, v94, v169
	v_fmac_f32_e32 v173, v160, v160
	v_fmac_f32_e32 v198, v149, v149
	v_mul_f32_e32 v210, v127, v127
	v_fmac_f32_e32 v210, v147, v147
	s_waitcnt lgkmcnt(0)
	v_add_f32_e32 v169, v184, v169
	v_cndmask_b32_e64 v184, v187, v172, s[42:43]
	v_cndmask_b32_e64 v172, v172, v187, s[42:43]
	ds_bpermute_b32 v172, v94, v172
	ds_bpermute_b32 v85, v94, v85
	s_or_b32 s6, s8, s6
	v_add_u32_e32 v84, s1, v84
	s_lshl_b32 s1, s6, 3
	s_waitcnt lgkmcnt(1)
	v_add_f32_e32 v172, v184, v172
	v_cndmask_b32_e64 v184, v189, v173, s[42:43]
	v_cndmask_b32_e64 v173, v173, v189, s[42:43]
	ds_bpermute_b32 v173, v94, v173
	s_waitcnt lgkmcnt(1)
	v_add_f32_e32 v85, v211, v85
	s_add_u32 s46, s30, s1
	s_addc_u32 s47, s31, 0
	s_waitcnt lgkmcnt(0)
	v_add_f32_e32 v173, v184, v173
	v_cndmask_b32_e64 v184, v196, v177, s[42:43]
	v_cndmask_b32_e64 v177, v177, v196, s[42:43]
	ds_bpermute_b32 v177, v94, v177
	s_waitcnt lgkmcnt(0)
	v_add_f32_e32 v177, v184, v177
	v_cndmask_b32_e64 v184, v198, v179, s[42:43]
	v_cndmask_b32_e64 v179, v179, v198, s[42:43]
	ds_bpermute_b32 v179, v94, v179
	s_waitcnt lgkmcnt(0)
	v_add_f32_e32 v179, v184, v179
	v_cndmask_b32_e64 v184, v209, v180, s[42:43]
	v_cndmask_b32_e64 v180, v180, v209, s[42:43]
	ds_bpermute_b32 v180, v94, v180
	s_waitcnt lgkmcnt(0)
	v_add_f32_e32 v180, v184, v180
	v_cndmask_b32_e64 v184, v210, v182, s[42:43]
	v_cndmask_b32_e64 v182, v182, v210, s[42:43]
	ds_bpermute_b32 v182, v94, v182
	s_waitcnt lgkmcnt(0)
	v_add_f32_e32 v182, v184, v182
	v_cndmask_b32_e64 v184, v177, v85, s[38:39]
	v_cndmask_b32_e64 v85, v85, v177, s[38:39]
	v_cndmask_b32_e64 v177, v179, v169, s[38:39]
	v_cndmask_b32_e64 v169, v169, v179, s[38:39]
	ds_bpermute_b32 v169, v93, v169
	ds_bpermute_b32 v85, v93, v85
	s_waitcnt lgkmcnt(1)
	v_add_f32_e32 v169, v177, v169
	v_cndmask_b32_e64 v177, v180, v172, s[38:39]
	v_cndmask_b32_e64 v172, v172, v180, s[38:39]
	ds_bpermute_b32 v172, v93, v172
	s_waitcnt lgkmcnt(1)
	v_add_f32_e32 v85, v184, v85
	s_waitcnt lgkmcnt(0)
	v_add_f32_e32 v172, v177, v172
	v_cndmask_b32_e64 v177, v182, v173, s[38:39]
	v_cndmask_b32_e64 v173, v173, v182, s[38:39]
	ds_bpermute_b32 v173, v93, v173
	s_waitcnt lgkmcnt(0)
	v_add_f32_e32 v173, v177, v173
	v_cndmask_b32_e64 v177, v172, v85, s[36:37]
	v_cndmask_b32_e64 v85, v85, v172, s[36:37]
	v_cndmask_b32_e64 v172, v173, v169, s[36:37]
	v_cndmask_b32_e64 v169, v169, v173, s[36:37]
	ds_bpermute_b32 v85, v90, v85
	ds_bpermute_b32 v169, v90, v169
	s_waitcnt lgkmcnt(1)
	v_add_f32_e32 v85, v177, v85
	s_waitcnt lgkmcnt(0)
	v_add_f32_e32 v169, v172, v169
	v_cndmask_b32_e64 v172, v169, v85, s[40:41]
	v_cndmask_b32_e64 v85, v85, v169, s[40:41]
	ds_bpermute_b32 v85, v91, v85
	s_waitcnt lgkmcnt(0)
	v_add_f32_e32 v169, v172, v85
	ds_bpermute_b32 v172, v92, v169
	v_ashrrev_i32_e32 v85, 31, v84
	s_and_saveexec_b64 s[48:49], s[44:45]
	s_cbranch_execz .LBB0_632
	v_lshlrev_b64 v[186:187], 7, v[84:85]
	s_waitcnt lgkmcnt(0)
	v_add_f32_e32 v172, v169, v172
	v_lshl_add_u64 v[186:187], s[46:47], 0, v[186:187]
	v_mov_b32_e32 v173, s92
	global_store_dwordx2 v[186:187], v[172:173], off sc1
	.p2align 6
	s_nop 0
	s_nop 0
	s_nop 0
	s_nop 0
